# pre-MFMA barrier taken four MFMAs (two accumulator chains) into the block instead of two, on top of v16
# baseline (speedup 1.0000x reference)
.LBB0_133:
	s_add_u32 vcc_lo, s0, 0xffffc000
	s_addc_u32 vcc_hi, s1, -1
	s_mov_b32 m0, s52
	s_nop 0
	global_load_lds_dwordx4 v158, vcc
	s_mov_b32 m0, s53
	s_nop 0
	global_load_lds_dwordx4 v160, vcc
	ds_read_b128 v[130:133], v224
	ds_read_b128 v[134:137], v224 offset:1024
	ds_read_b128 v[138:141], v224 offset:2048
	ds_read_b128 v[142:145], v224 offset:3072
	ds_read_b128 v[146:149], v224 offset:16384
	ds_read_b128 v[162:165], v224 offset:17408
	ds_read_b128 v[166:169], v224 offset:18432
	ds_read_b128 v[170:173], v224 offset:19456
	ds_read_b128 v[174:177], v225
	ds_read_b128 v[178:181], v225 offset:1024
	ds_read_b128 v[182:185], v225 offset:2048
	ds_read_b128 v[186:189], v225 offset:3072
	ds_read_b128 v[190:193], v225 offset:4096
	ds_read_b128 v[204:207], v225 offset:5120
	ds_read_b128 v[208:211], v225 offset:6144
	ds_read_b128 v[212:215], v225 offset:7168
	s_add_u32 s4, s0, 0x100
	s_addc_u32 s5, s1, 0
	s_add_i32 s58, 0, 0x10000
	s_cmp_eq_u32 s57, 28
	s_cselect_b32 s35, s27, s5
	s_cselect_b32 s34, s26, s4
	s_cselect_b32 s31, s25, s51
	s_cselect_b32 s30, s37, s50
	s_add_i32 s59, 0, 0x14000
	s_add_i32 m0, s38, 0xc000
	s_nop 0
	global_load_lds_dwordx4 v158, s[0:1]
	s_add_i32 m0, s38, 0xe000
	s_nop 0
	global_load_lds_dwordx4 v160, s[0:1]
	s_waitcnt vmcnt(8)
	s_waitcnt lgkmcnt(0)
	v_mfma_f32_16x16x32_bf16 v[126:129], v[130:133], v[174:177], v[126:129]
	v_mfma_f32_16x16x32_bf16 v[126:129], v[134:137], v[178:181], v[126:129]
	v_mfma_f32_16x16x32_bf16 v[122:125], v[142:145], v[178:181], v[122:125]
	v_mfma_f32_16x16x32_bf16 v[122:125], v[138:141], v[174:177], v[122:125]
	s_barrier
	s_setprio 1
	v_mfma_f32_16x16x32_bf16 v[106:109], v[138:141], v[182:185], v[106:109]
	v_mfma_f32_16x16x32_bf16 v[106:109], v[142:145], v[186:189], v[106:109]
	v_mfma_f32_16x16x32_bf16 v[110:113], v[134:137], v[186:189], v[110:113]
	v_mfma_f32_16x16x32_bf16 v[110:113], v[130:133], v[182:185], v[110:113]
	v_mfma_f32_16x16x32_bf16 v[94:97], v[130:133], v[190:193], v[94:97]
	v_mfma_f32_16x16x32_bf16 v[94:97], v[134:137], v[204:207], v[94:97]
	v_mfma_f32_16x16x32_bf16 v[90:93], v[142:145], v[204:207], v[90:93]
	v_mfma_f32_16x16x32_bf16 v[90:93], v[138:141], v[190:193], v[90:93]
	v_mfma_f32_16x16x32_bf16 v[74:77], v[138:141], v[208:211], v[74:77]
	v_mfma_f32_16x16x32_bf16 v[74:77], v[142:145], v[212:215], v[74:77]
	v_mfma_f32_16x16x32_bf16 v[78:81], v[134:137], v[212:215], v[78:81]
	v_mfma_f32_16x16x32_bf16 v[78:81], v[130:133], v[208:211], v[78:81]
	v_mfma_f32_16x16x32_bf16 v[118:121], v[146:149], v[174:177], v[118:121]
	v_mfma_f32_16x16x32_bf16 v[118:121], v[162:165], v[178:181], v[118:121]
	v_mfma_f32_16x16x32_bf16 v[114:117], v[170:173], v[178:181], v[114:117]
	v_mfma_f32_16x16x32_bf16 v[114:117], v[166:169], v[174:177], v[114:117]
	v_mfma_f32_16x16x32_bf16 v[98:101], v[166:169], v[182:185], v[98:101]
	v_mfma_f32_16x16x32_bf16 v[98:101], v[170:173], v[186:189], v[98:101]
	v_mfma_f32_16x16x32_bf16 v[102:105], v[162:165], v[186:189], v[102:105]
	v_mfma_f32_16x16x32_bf16 v[102:105], v[146:149], v[182:185], v[102:105]
	v_mfma_f32_16x16x32_bf16 v[86:89], v[146:149], v[190:193], v[86:89]
	v_mfma_f32_16x16x32_bf16 v[86:89], v[162:165], v[204:207], v[86:89]
	v_mfma_f32_16x16x32_bf16 v[82:85], v[170:173], v[204:207], v[82:85]
	v_mfma_f32_16x16x32_bf16 v[82:85], v[166:169], v[190:193], v[82:85]
	v_mfma_f32_16x16x32_bf16 v[66:69], v[166:169], v[208:211], v[66:69]
	v_mfma_f32_16x16x32_bf16 v[66:69], v[170:173], v[212:215], v[66:69]
	v_mfma_f32_16x16x32_bf16 v[70:73], v[162:165], v[212:215], v[70:73]
	v_mfma_f32_16x16x32_bf16 v[70:73], v[146:149], v[208:211], v[70:73]
	s_setprio 0
	s_barrier
	ds_read_b128 v[174:177], v225 offset:16384
	ds_read_b128 v[178:181], v225 offset:17408
	ds_read_b128 v[182:185], v225 offset:18432
	ds_read_b128 v[186:189], v225 offset:19456
	ds_read_b128 v[190:193], v225 offset:20480
	ds_read_b128 v[204:207], v225 offset:21504
	ds_read_b128 v[208:211], v225 offset:22528
	ds_read_b128 v[212:215], v225 offset:23552
	s_add_i32 s0, s58, s15
	s_mov_b32 m0, s0
	s_nop 0
	global_load_lds_dwordx4 v152, s[30:31]
	s_add_i32 m0, s0, 0x2000
	s_add_u32 s0, s30, 0x80000
	s_addc_u32 s1, s31, 0
	s_add_i32 s58, s59, s15
	global_load_lds_dwordx4 v156, s[30:31]
	s_mov_b32 m0, s58
	s_nop 0
	global_load_lds_dwordx4 v152, s[0:1]
	s_add_i32 m0, s58, 0x2000
	s_nop 0
	global_load_lds_dwordx4 v156, s[0:1]
	s_waitcnt vmcnt(6)
	s_waitcnt lgkmcnt(0)
	v_mfma_f32_16x16x32_bf16 v[62:65], v[130:133], v[174:177], v[62:65]
	v_mfma_f32_16x16x32_bf16 v[62:65], v[134:137], v[178:181], v[62:65]
	v_mfma_f32_16x16x32_bf16 v[58:61], v[142:145], v[178:181], v[58:61]
	v_mfma_f32_16x16x32_bf16 v[58:61], v[138:141], v[174:177], v[58:61]
	s_barrier
	s_setprio 1
	v_mfma_f32_16x16x32_bf16 v[42:45], v[138:141], v[182:185], v[42:45]
	v_mfma_f32_16x16x32_bf16 v[42:45], v[142:145], v[186:189], v[42:45]
	v_mfma_f32_16x16x32_bf16 v[46:49], v[134:137], v[186:189], v[46:49]
	v_mfma_f32_16x16x32_bf16 v[46:49], v[130:133], v[182:185], v[46:49]
	v_mfma_f32_16x16x32_bf16 v[30:33], v[130:133], v[190:193], v[30:33]
	v_mfma_f32_16x16x32_bf16 v[30:33], v[134:137], v[204:207], v[30:33]
	v_mfma_f32_16x16x32_bf16 v[26:29], v[142:145], v[204:207], v[26:29]
	v_mfma_f32_16x16x32_bf16 v[26:29], v[138:141], v[190:193], v[26:29]
	v_mfma_f32_16x16x32_bf16 v[10:13], v[138:141], v[208:211], v[10:13]
	v_mfma_f32_16x16x32_bf16 v[10:13], v[142:145], v[212:215], v[10:13]
	v_mfma_f32_16x16x32_bf16 v[14:17], v[134:137], v[212:215], v[14:17]
	v_mfma_f32_16x16x32_bf16 v[14:17], v[130:133], v[208:211], v[14:17]
	v_mfma_f32_16x16x32_bf16 v[54:57], v[146:149], v[174:177], v[54:57]
	v_mfma_f32_16x16x32_bf16 v[54:57], v[162:165], v[178:181], v[54:57]
	v_mfma_f32_16x16x32_bf16 v[50:53], v[170:173], v[178:181], v[50:53]
	v_mfma_f32_16x16x32_bf16 v[50:53], v[166:169], v[174:177], v[50:53]
	v_mfma_f32_16x16x32_bf16 v[34:37], v[166:169], v[182:185], v[34:37]
	v_mfma_f32_16x16x32_bf16 v[34:37], v[170:173], v[186:189], v[34:37]
	v_mfma_f32_16x16x32_bf16 v[38:41], v[162:165], v[186:189], v[38:41]
	v_mfma_f32_16x16x32_bf16 v[38:41], v[146:149], v[182:185], v[38:41]
	v_mfma_f32_16x16x32_bf16 v[22:25], v[146:149], v[190:193], v[22:25]
	v_mfma_f32_16x16x32_bf16 v[22:25], v[162:165], v[204:207], v[22:25]
	v_mfma_f32_16x16x32_bf16 v[18:21], v[170:173], v[204:207], v[18:21]
	v_mfma_f32_16x16x32_bf16 v[18:21], v[166:169], v[190:193], v[18:21]
	v_mfma_f32_16x16x32_bf16 v[2:5], v[166:169], v[208:211], v[2:5]
	v_mfma_f32_16x16x32_bf16 v[2:5], v[170:173], v[212:215], v[2:5]
	v_mfma_f32_16x16x32_bf16 v[6:9], v[162:165], v[212:215], v[6:9]
	v_mfma_f32_16x16x32_bf16 v[6:9], v[146:149], v[208:211], v[6:9]
	s_setprio 0
	s_barrier
	s_mov_b32 m0, s38
	s_nop 0
	global_load_lds_dwordx4 v150, s[34:35]
	s_mov_b32 m0, s39
	s_nop 0
	global_load_lds_dwordx4 v154, s[34:35]
	ds_read_b128 v[130:133], v224 offset:32768
	ds_read_b128 v[134:137], v224 offset:33792
	ds_read_b128 v[138:141], v224 offset:34816
	ds_read_b128 v[142:145], v224 offset:35840
	ds_read_b128 v[146:149], v224 offset:49152
	ds_read_b128 v[162:165], v224 offset:50176
	ds_read_b128 v[166:169], v224 offset:51200
	ds_read_b128 v[170:173], v224 offset:52224
	ds_read_b128 v[174:177], v225 offset:32768
	ds_read_b128 v[178:181], v225 offset:33792
	ds_read_b128 v[182:185], v225 offset:34816
	ds_read_b128 v[186:189], v225 offset:35840
	ds_read_b128 v[190:193], v225 offset:36864
	ds_read_b128 v[204:207], v225 offset:37888
	ds_read_b128 v[208:211], v225 offset:38912
	ds_read_b128 v[212:215], v225 offset:39936
	s_add_i32 s58, 0, 0x18000
	s_add_i32 s59, 0, 0x1c000
	s_add_u32 s0, s34, 0x4000
	s_addc_u32 s1, s35, 0
	s_mov_b32 m0, s40
	s_nop 0
	global_load_lds_dwordx4 v150, s[0:1]
	s_mov_b32 m0, s41
	s_nop 0
	global_load_lds_dwordx4 v154, s[0:1]
	s_waitcnt vmcnt(8)
	s_waitcnt lgkmcnt(0)
	v_mfma_f32_16x16x32_bf16 v[126:129], v[130:133], v[174:177], v[126:129]
	v_mfma_f32_16x16x32_bf16 v[126:129], v[134:137], v[178:181], v[126:129]
	v_mfma_f32_16x16x32_bf16 v[122:125], v[142:145], v[178:181], v[122:125]
	v_mfma_f32_16x16x32_bf16 v[122:125], v[138:141], v[174:177], v[122:125]
	s_barrier
	s_setprio 1
	v_mfma_f32_16x16x32_bf16 v[106:109], v[138:141], v[182:185], v[106:109]
	v_mfma_f32_16x16x32_bf16 v[106:109], v[142:145], v[186:189], v[106:109]
	v_mfma_f32_16x16x32_bf16 v[110:113], v[134:137], v[186:189], v[110:113]
	v_mfma_f32_16x16x32_bf16 v[110:113], v[130:133], v[182:185], v[110:113]
	v_mfma_f32_16x16x32_bf16 v[94:97], v[130:133], v[190:193], v[94:97]
	v_mfma_f32_16x16x32_bf16 v[94:97], v[134:137], v[204:207], v[94:97]
	v_mfma_f32_16x16x32_bf16 v[90:93], v[142:145], v[204:207], v[90:93]
	v_mfma_f32_16x16x32_bf16 v[90:93], v[138:141], v[190:193], v[90:93]
	v_mfma_f32_16x16x32_bf16 v[74:77], v[138:141], v[208:211], v[74:77]
	v_mfma_f32_16x16x32_bf16 v[74:77], v[142:145], v[212:215], v[74:77]
	v_mfma_f32_16x16x32_bf16 v[78:81], v[134:137], v[212:215], v[78:81]
	v_mfma_f32_16x16x32_bf16 v[78:81], v[130:133], v[208:211], v[78:81]
	v_mfma_f32_16x16x32_bf16 v[118:121], v[146:149], v[174:177], v[118:121]
	v_mfma_f32_16x16x32_bf16 v[118:121], v[162:165], v[178:181], v[118:121]
	v_mfma_f32_16x16x32_bf16 v[114:117], v[170:173], v[178:181], v[114:117]
	v_mfma_f32_16x16x32_bf16 v[114:117], v[166:169], v[174:177], v[114:117]
	v_mfma_f32_16x16x32_bf16 v[98:101], v[166:169], v[182:185], v[98:101]
	v_mfma_f32_16x16x32_bf16 v[98:101], v[170:173], v[186:189], v[98:101]
	v_mfma_f32_16x16x32_bf16 v[102:105], v[162:165], v[186:189], v[102:105]
	v_mfma_f32_16x16x32_bf16 v[102:105], v[146:149], v[182:185], v[102:105]
	v_mfma_f32_16x16x32_bf16 v[86:89], v[146:149], v[190:193], v[86:89]
	v_mfma_f32_16x16x32_bf16 v[86:89], v[162:165], v[204:207], v[86:89]
	v_mfma_f32_16x16x32_bf16 v[82:85], v[170:173], v[204:207], v[82:85]
	v_mfma_f32_16x16x32_bf16 v[82:85], v[166:169], v[190:193], v[82:85]
	v_mfma_f32_16x16x32_bf16 v[66:69], v[166:169], v[208:211], v[66:69]
	v_mfma_f32_16x16x32_bf16 v[66:69], v[170:173], v[212:215], v[66:69]
	v_mfma_f32_16x16x32_bf16 v[70:73], v[162:165], v[212:215], v[70:73]
	v_mfma_f32_16x16x32_bf16 v[70:73], v[146:149], v[208:211], v[70:73]
	s_setprio 0
	s_barrier
	ds_read_b128 v[174:177], v225 offset:49152
	ds_read_b128 v[178:181], v225 offset:50176
	ds_read_b128 v[182:185], v225 offset:51200
	ds_read_b128 v[186:189], v225 offset:52224
	ds_read_b128 v[190:193], v225 offset:53248
	ds_read_b128 v[204:207], v225 offset:54272
	ds_read_b128 v[208:211], v225 offset:55296
	ds_read_b128 v[212:215], v225 offset:56320
	s_add_i32 s0, s58, s15
	s_add_u32 vcc_lo, s30, s94
	s_addc_u32 vcc_hi, s31, s95
	s_mov_b32 m0, s0
	s_nop 0
	global_load_lds_dwordx4 v152, vcc
	s_add_i32 m0, s0, 0x2000
	s_add_u32 s0, s30, 0x80080
	s_addc_u32 s1, s31, 0
	s_add_i32 s30, s59, s15
	global_load_lds_dwordx4 v156, vcc
	s_mov_b32 m0, s30
	s_nop 0
	global_load_lds_dwordx4 v152, s[0:1]
	s_add_i32 m0, s30, 0x2000
	s_nop 0
	global_load_lds_dwordx4 v156, s[0:1]
	s_waitcnt vmcnt(6)
	s_waitcnt lgkmcnt(0)
	v_mfma_f32_16x16x32_bf16 v[62:65], v[130:133], v[174:177], v[62:65]
	v_mfma_f32_16x16x32_bf16 v[62:65], v[134:137], v[178:181], v[62:65]
	v_mfma_f32_16x16x32_bf16 v[58:61], v[142:145], v[178:181], v[58:61]
	v_mfma_f32_16x16x32_bf16 v[58:61], v[138:141], v[174:177], v[58:61]
	s_barrier
	s_setprio 1
	v_mfma_f32_16x16x32_bf16 v[42:45], v[138:141], v[182:185], v[42:45]
	v_mfma_f32_16x16x32_bf16 v[42:45], v[142:145], v[186:189], v[42:45]
	v_mfma_f32_16x16x32_bf16 v[46:49], v[134:137], v[186:189], v[46:49]
	v_mfma_f32_16x16x32_bf16 v[46:49], v[130:133], v[182:185], v[46:49]
	v_mfma_f32_16x16x32_bf16 v[30:33], v[130:133], v[190:193], v[30:33]
	v_mfma_f32_16x16x32_bf16 v[30:33], v[134:137], v[204:207], v[30:33]
	v_mfma_f32_16x16x32_bf16 v[26:29], v[142:145], v[204:207], v[26:29]
	v_mfma_f32_16x16x32_bf16 v[26:29], v[138:141], v[190:193], v[26:29]
	v_mfma_f32_16x16x32_bf16 v[10:13], v[138:141], v[208:211], v[10:13]
	v_mfma_f32_16x16x32_bf16 v[10:13], v[142:145], v[212:215], v[10:13]
	s_add_i32 s57, s57, 2
	v_mfma_f32_16x16x32_bf16 v[14:17], v[134:137], v[212:215], v[14:17]
	v_mfma_f32_16x16x32_bf16 v[14:17], v[130:133], v[208:211], v[14:17]
	s_add_u32 s50, s50, 0x100
	v_mfma_f32_16x16x32_bf16 v[54:57], v[146:149], v[174:177], v[54:57]
	v_mfma_f32_16x16x32_bf16 v[54:57], v[162:165], v[178:181], v[54:57]
	s_addc_u32 s51, s51, 0
	v_mfma_f32_16x16x32_bf16 v[50:53], v[170:173], v[178:181], v[50:53]
	v_mfma_f32_16x16x32_bf16 v[50:53], v[166:169], v[174:177], v[50:53]
	s_cmp_gt_u32 s57, 29
	v_mfma_f32_16x16x32_bf16 v[34:37], v[166:169], v[182:185], v[34:37]
	v_mfma_f32_16x16x32_bf16 v[34:37], v[170:173], v[186:189], v[34:37]
	s_mov_b64 s[0:1], s[4:5]
	v_mfma_f32_16x16x32_bf16 v[38:41], v[162:165], v[186:189], v[38:41]
	v_mfma_f32_16x16x32_bf16 v[38:41], v[146:149], v[182:185], v[38:41]
	v_mfma_f32_16x16x32_bf16 v[22:25], v[146:149], v[190:193], v[22:25]
	v_mfma_f32_16x16x32_bf16 v[22:25], v[162:165], v[204:207], v[22:25]
	v_mfma_f32_16x16x32_bf16 v[18:21], v[170:173], v[204:207], v[18:21]
	v_mfma_f32_16x16x32_bf16 v[18:21], v[166:169], v[190:193], v[18:21]
	v_mfma_f32_16x16x32_bf16 v[2:5], v[166:169], v[208:211], v[2:5]
	v_mfma_f32_16x16x32_bf16 v[2:5], v[170:173], v[212:215], v[2:5]
	v_mfma_f32_16x16x32_bf16 v[6:9], v[162:165], v[212:215], v[6:9]
	v_mfma_f32_16x16x32_bf16 v[6:9], v[146:149], v[208:211], v[6:9]
	s_setprio 0
	s_barrier
	s_cbranch_scc0 .LBB0_133

.LBB0_305:
	s_add_u32 vcc_lo, s0, 0xffffc000
	s_addc_u32 vcc_hi, s1, -1
	s_mov_b32 m0, s62
	s_nop 0
	global_load_lds_dwordx4 v178, vcc
	s_mov_b32 m0, s63
	s_nop 0
	global_load_lds_dwordx4 v180, vcc
	ds_read_b128 v[130:133], v226
	ds_read_b128 v[134:137], v226 offset:1024
	ds_read_b128 v[138:141], v226 offset:2048
	ds_read_b128 v[142:145], v226 offset:3072
	ds_read_b128 v[146:149], v226 offset:16384
	ds_read_b128 v[150:153], v226 offset:17408
	ds_read_b128 v[154:157], v226 offset:18432
	ds_read_b128 v[158:161], v226 offset:19456
	ds_read_b128 v[162:165], v227
	ds_read_b128 v[166:169], v227 offset:1024
	ds_read_b128 v[182:185], v227 offset:2048
	ds_read_b128 v[186:189], v227 offset:3072
	ds_read_b128 v[190:193], v227 offset:4096
	ds_read_b128 v[204:207], v227 offset:5120
	ds_read_b128 v[208:211], v227 offset:6144
	ds_read_b128 v[212:215], v227 offset:7168
	s_add_i32 s71, s38, 2
	s_add_u32 s4, s0, 0x100
	s_addc_u32 s5, s1, 0
	s_add_i32 s73, 0, 0x10000
	s_cmp_eq_u32 s37, s38
	s_cselect_b32 s41, s31, s5
	s_cselect_b32 s40, s30, s4
	s_cselect_b32 s39, s25, s70
	s_cselect_b32 s38, s27, s51
	s_add_i32 s75, 0, 0x14000
	s_add_i32 m0, s56, 0xc000
	s_nop 0
	global_load_lds_dwordx4 v178, s[0:1]
	s_add_i32 m0, s56, 0xe000
	s_nop 0
	global_load_lds_dwordx4 v180, s[0:1]
	s_waitcnt vmcnt(8)
	s_waitcnt lgkmcnt(0)
	v_mfma_f32_16x16x32_bf16 v[126:129], v[130:133], v[162:165], v[126:129]
	v_mfma_f32_16x16x32_bf16 v[126:129], v[134:137], v[166:169], v[126:129]
	v_mfma_f32_16x16x32_bf16 v[122:125], v[142:145], v[166:169], v[122:125]
	v_mfma_f32_16x16x32_bf16 v[122:125], v[138:141], v[162:165], v[122:125]
	s_barrier
	s_setprio 1
	v_mfma_f32_16x16x32_bf16 v[106:109], v[138:141], v[182:185], v[106:109]
	v_mfma_f32_16x16x32_bf16 v[106:109], v[142:145], v[186:189], v[106:109]
	v_mfma_f32_16x16x32_bf16 v[110:113], v[134:137], v[186:189], v[110:113]
	v_mfma_f32_16x16x32_bf16 v[110:113], v[130:133], v[182:185], v[110:113]
	v_mfma_f32_16x16x32_bf16 v[94:97], v[130:133], v[190:193], v[94:97]
	v_mfma_f32_16x16x32_bf16 v[94:97], v[134:137], v[204:207], v[94:97]
	v_mfma_f32_16x16x32_bf16 v[90:93], v[142:145], v[204:207], v[90:93]
	v_mfma_f32_16x16x32_bf16 v[90:93], v[138:141], v[190:193], v[90:93]
	v_mfma_f32_16x16x32_bf16 v[74:77], v[138:141], v[208:211], v[74:77]
	v_mfma_f32_16x16x32_bf16 v[74:77], v[142:145], v[212:215], v[74:77]
	v_mfma_f32_16x16x32_bf16 v[78:81], v[134:137], v[212:215], v[78:81]
	v_mfma_f32_16x16x32_bf16 v[78:81], v[130:133], v[208:211], v[78:81]
	v_mfma_f32_16x16x32_bf16 v[118:121], v[146:149], v[162:165], v[118:121]
	v_mfma_f32_16x16x32_bf16 v[118:121], v[150:153], v[166:169], v[118:121]
	v_mfma_f32_16x16x32_bf16 v[114:117], v[158:161], v[166:169], v[114:117]
	v_mfma_f32_16x16x32_bf16 v[114:117], v[154:157], v[162:165], v[114:117]
	v_mfma_f32_16x16x32_bf16 v[98:101], v[154:157], v[182:185], v[98:101]
	v_mfma_f32_16x16x32_bf16 v[98:101], v[158:161], v[186:189], v[98:101]
	v_mfma_f32_16x16x32_bf16 v[102:105], v[150:153], v[186:189], v[102:105]
	v_mfma_f32_16x16x32_bf16 v[102:105], v[146:149], v[182:185], v[102:105]
	v_mfma_f32_16x16x32_bf16 v[86:89], v[146:149], v[190:193], v[86:89]
	v_mfma_f32_16x16x32_bf16 v[86:89], v[150:153], v[204:207], v[86:89]
	v_mfma_f32_16x16x32_bf16 v[82:85], v[158:161], v[204:207], v[82:85]
	v_mfma_f32_16x16x32_bf16 v[82:85], v[154:157], v[190:193], v[82:85]
	v_mfma_f32_16x16x32_bf16 v[66:69], v[154:157], v[208:211], v[66:69]
	v_mfma_f32_16x16x32_bf16 v[66:69], v[158:161], v[212:215], v[66:69]
	v_mfma_f32_16x16x32_bf16 v[70:73], v[150:153], v[212:215], v[70:73]
	v_mfma_f32_16x16x32_bf16 v[70:73], v[146:149], v[208:211], v[70:73]
	s_setprio 0
	s_barrier
	ds_read_b128 v[162:165], v227 offset:16384
	ds_read_b128 v[166:169], v227 offset:17408
	ds_read_b128 v[182:185], v227 offset:18432
	ds_read_b128 v[186:189], v227 offset:19456
	ds_read_b128 v[190:193], v227 offset:20480
	ds_read_b128 v[204:207], v227 offset:21504
	ds_read_b128 v[208:211], v227 offset:22528
	ds_read_b128 v[212:215], v227 offset:23552
	s_add_i32 s0, s73, s15
	s_mov_b32 m0, s0
	s_nop 0
	global_load_lds_dwordx4 v172, s[38:39]
	s_add_i32 m0, s0, 0x2000
	s_add_u32 s0, s38, 0x80000
	s_addc_u32 s1, s39, 0
	s_add_i32 s73, s75, s15
	global_load_lds_dwordx4 v176, s[38:39]
	s_mov_b32 m0, s73
	s_nop 0
	global_load_lds_dwordx4 v172, s[0:1]
	s_add_i32 m0, s73, 0x2000
	s_nop 0
	global_load_lds_dwordx4 v176, s[0:1]
	s_waitcnt vmcnt(6)
	s_waitcnt lgkmcnt(0)
	v_mfma_f32_16x16x32_bf16 v[62:65], v[130:133], v[162:165], v[62:65]
	v_mfma_f32_16x16x32_bf16 v[62:65], v[134:137], v[166:169], v[62:65]
	v_mfma_f32_16x16x32_bf16 v[58:61], v[142:145], v[166:169], v[58:61]
	v_mfma_f32_16x16x32_bf16 v[58:61], v[138:141], v[162:165], v[58:61]
	s_barrier
	s_setprio 1
	v_mfma_f32_16x16x32_bf16 v[42:45], v[138:141], v[182:185], v[42:45]
	v_mfma_f32_16x16x32_bf16 v[42:45], v[142:145], v[186:189], v[42:45]
	v_mfma_f32_16x16x32_bf16 v[46:49], v[134:137], v[186:189], v[46:49]
	v_mfma_f32_16x16x32_bf16 v[46:49], v[130:133], v[182:185], v[46:49]
	v_mfma_f32_16x16x32_bf16 v[30:33], v[130:133], v[190:193], v[30:33]
	v_mfma_f32_16x16x32_bf16 v[30:33], v[134:137], v[204:207], v[30:33]
	v_mfma_f32_16x16x32_bf16 v[26:29], v[142:145], v[204:207], v[26:29]
	v_mfma_f32_16x16x32_bf16 v[26:29], v[138:141], v[190:193], v[26:29]
	v_mfma_f32_16x16x32_bf16 v[10:13], v[138:141], v[208:211], v[10:13]
	v_mfma_f32_16x16x32_bf16 v[10:13], v[142:145], v[212:215], v[10:13]
	v_mfma_f32_16x16x32_bf16 v[14:17], v[134:137], v[212:215], v[14:17]
	v_mfma_f32_16x16x32_bf16 v[14:17], v[130:133], v[208:211], v[14:17]
	v_mfma_f32_16x16x32_bf16 v[54:57], v[146:149], v[162:165], v[54:57]
	v_mfma_f32_16x16x32_bf16 v[54:57], v[150:153], v[166:169], v[54:57]
	v_mfma_f32_16x16x32_bf16 v[50:53], v[158:161], v[166:169], v[50:53]
	v_mfma_f32_16x16x32_bf16 v[50:53], v[154:157], v[162:165], v[50:53]
	v_mfma_f32_16x16x32_bf16 v[34:37], v[154:157], v[182:185], v[34:37]
	v_mfma_f32_16x16x32_bf16 v[34:37], v[158:161], v[186:189], v[34:37]
	v_mfma_f32_16x16x32_bf16 v[38:41], v[150:153], v[186:189], v[38:41]
	v_mfma_f32_16x16x32_bf16 v[38:41], v[146:149], v[182:185], v[38:41]
	v_mfma_f32_16x16x32_bf16 v[22:25], v[146:149], v[190:193], v[22:25]
	v_mfma_f32_16x16x32_bf16 v[22:25], v[150:153], v[204:207], v[22:25]
	v_mfma_f32_16x16x32_bf16 v[18:21], v[158:161], v[204:207], v[18:21]
	v_mfma_f32_16x16x32_bf16 v[18:21], v[154:157], v[190:193], v[18:21]
	v_mfma_f32_16x16x32_bf16 v[2:5], v[154:157], v[208:211], v[2:5]
	v_mfma_f32_16x16x32_bf16 v[2:5], v[158:161], v[212:215], v[2:5]
	v_mfma_f32_16x16x32_bf16 v[6:9], v[150:153], v[212:215], v[6:9]
	v_mfma_f32_16x16x32_bf16 v[6:9], v[146:149], v[208:211], v[6:9]
	s_setprio 0
	s_barrier
	s_mov_b32 m0, s56
	s_nop 0
	global_load_lds_dwordx4 v170, s[40:41]
	s_mov_b32 m0, s57
	s_nop 0
	global_load_lds_dwordx4 v174, s[40:41]
	ds_read_b128 v[130:133], v226 offset:32768
	ds_read_b128 v[134:137], v226 offset:33792
	ds_read_b128 v[138:141], v226 offset:34816
	ds_read_b128 v[142:145], v226 offset:35840
	ds_read_b128 v[146:149], v226 offset:49152
	ds_read_b128 v[150:153], v226 offset:50176
	ds_read_b128 v[154:157], v226 offset:51200
	ds_read_b128 v[158:161], v226 offset:52224
	ds_read_b128 v[162:165], v227 offset:32768
	ds_read_b128 v[166:169], v227 offset:33792
	ds_read_b128 v[182:185], v227 offset:34816
	ds_read_b128 v[186:189], v227 offset:35840
	ds_read_b128 v[190:193], v227 offset:36864
	ds_read_b128 v[204:207], v227 offset:37888
	ds_read_b128 v[208:211], v227 offset:38912
	ds_read_b128 v[212:215], v227 offset:39936
	s_add_i32 s73, 0, 0x18000
	s_add_i32 s75, 0, 0x1c000
	s_add_u32 s0, s40, 0x4000
	s_addc_u32 s1, s41, 0
	s_mov_b32 m0, s58
	s_nop 0
	global_load_lds_dwordx4 v170, s[0:1]
	s_mov_b32 m0, s59
	s_nop 0
	global_load_lds_dwordx4 v174, s[0:1]
	s_waitcnt vmcnt(8)
	s_waitcnt lgkmcnt(0)
	v_mfma_f32_16x16x32_bf16 v[126:129], v[130:133], v[162:165], v[126:129]
	v_mfma_f32_16x16x32_bf16 v[126:129], v[134:137], v[166:169], v[126:129]
	v_mfma_f32_16x16x32_bf16 v[122:125], v[142:145], v[166:169], v[122:125]
	v_mfma_f32_16x16x32_bf16 v[122:125], v[138:141], v[162:165], v[122:125]
	s_barrier
	s_setprio 1
	v_mfma_f32_16x16x32_bf16 v[106:109], v[138:141], v[182:185], v[106:109]
	v_mfma_f32_16x16x32_bf16 v[106:109], v[142:145], v[186:189], v[106:109]
	v_mfma_f32_16x16x32_bf16 v[110:113], v[134:137], v[186:189], v[110:113]
	v_mfma_f32_16x16x32_bf16 v[110:113], v[130:133], v[182:185], v[110:113]
	v_mfma_f32_16x16x32_bf16 v[94:97], v[130:133], v[190:193], v[94:97]
	v_mfma_f32_16x16x32_bf16 v[94:97], v[134:137], v[204:207], v[94:97]
	v_mfma_f32_16x16x32_bf16 v[90:93], v[142:145], v[204:207], v[90:93]
	v_mfma_f32_16x16x32_bf16 v[90:93], v[138:141], v[190:193], v[90:93]
	v_mfma_f32_16x16x32_bf16 v[74:77], v[138:141], v[208:211], v[74:77]
	v_mfma_f32_16x16x32_bf16 v[74:77], v[142:145], v[212:215], v[74:77]
	v_mfma_f32_16x16x32_bf16 v[78:81], v[134:137], v[212:215], v[78:81]
	v_mfma_f32_16x16x32_bf16 v[78:81], v[130:133], v[208:211], v[78:81]
	v_mfma_f32_16x16x32_bf16 v[118:121], v[146:149], v[162:165], v[118:121]
	v_mfma_f32_16x16x32_bf16 v[118:121], v[150:153], v[166:169], v[118:121]
	v_mfma_f32_16x16x32_bf16 v[114:117], v[158:161], v[166:169], v[114:117]
	v_mfma_f32_16x16x32_bf16 v[114:117], v[154:157], v[162:165], v[114:117]
	v_mfma_f32_16x16x32_bf16 v[98:101], v[154:157], v[182:185], v[98:101]
	v_mfma_f32_16x16x32_bf16 v[98:101], v[158:161], v[186:189], v[98:101]
	v_mfma_f32_16x16x32_bf16 v[102:105], v[150:153], v[186:189], v[102:105]
	v_mfma_f32_16x16x32_bf16 v[102:105], v[146:149], v[182:185], v[102:105]
	v_mfma_f32_16x16x32_bf16 v[86:89], v[146:149], v[190:193], v[86:89]
	v_mfma_f32_16x16x32_bf16 v[86:89], v[150:153], v[204:207], v[86:89]
	v_mfma_f32_16x16x32_bf16 v[82:85], v[158:161], v[204:207], v[82:85]
	v_mfma_f32_16x16x32_bf16 v[82:85], v[154:157], v[190:193], v[82:85]
	v_mfma_f32_16x16x32_bf16 v[66:69], v[154:157], v[208:211], v[66:69]
	v_mfma_f32_16x16x32_bf16 v[66:69], v[158:161], v[212:215], v[66:69]
	v_mfma_f32_16x16x32_bf16 v[70:73], v[150:153], v[212:215], v[70:73]
	v_mfma_f32_16x16x32_bf16 v[70:73], v[146:149], v[208:211], v[70:73]
	s_setprio 0
	s_barrier
	ds_read_b128 v[162:165], v227 offset:49152
	ds_read_b128 v[166:169], v227 offset:50176
	ds_read_b128 v[182:185], v227 offset:51200
	ds_read_b128 v[186:189], v227 offset:52224
	ds_read_b128 v[190:193], v227 offset:53248
	ds_read_b128 v[204:207], v227 offset:54272
	ds_read_b128 v[208:211], v227 offset:55296
	ds_read_b128 v[212:215], v227 offset:56320
	s_add_i32 s0, s73, s15
	s_add_u32 vcc_lo, s38, s94
	s_addc_u32 vcc_hi, s39, s95
	s_mov_b32 m0, s0
	s_nop 0
	global_load_lds_dwordx4 v172, vcc
	s_add_i32 m0, s0, 0x2000
	s_add_u32 s0, s38, 0x80080
	s_addc_u32 s1, s39, 0
	s_add_i32 s38, s75, s15
	global_load_lds_dwordx4 v176, vcc
	s_mov_b32 m0, s38
	s_nop 0
	global_load_lds_dwordx4 v172, s[0:1]
	s_add_i32 m0, s38, 0x2000
	s_nop 0
	global_load_lds_dwordx4 v176, s[0:1]
	s_waitcnt vmcnt(6)
	s_waitcnt lgkmcnt(0)
	v_mfma_f32_16x16x32_bf16 v[62:65], v[130:133], v[162:165], v[62:65]
	v_mfma_f32_16x16x32_bf16 v[62:65], v[134:137], v[166:169], v[62:65]
	v_mfma_f32_16x16x32_bf16 v[58:61], v[142:145], v[166:169], v[58:61]
	v_mfma_f32_16x16x32_bf16 v[58:61], v[138:141], v[162:165], v[58:61]
	s_barrier
	s_setprio 1
	v_mfma_f32_16x16x32_bf16 v[42:45], v[138:141], v[182:185], v[42:45]
	v_mfma_f32_16x16x32_bf16 v[42:45], v[142:145], v[186:189], v[42:45]
	v_mfma_f32_16x16x32_bf16 v[46:49], v[134:137], v[186:189], v[46:49]
	v_mfma_f32_16x16x32_bf16 v[46:49], v[130:133], v[182:185], v[46:49]
	v_mfma_f32_16x16x32_bf16 v[30:33], v[130:133], v[190:193], v[30:33]
	v_mfma_f32_16x16x32_bf16 v[30:33], v[134:137], v[204:207], v[30:33]
	v_mfma_f32_16x16x32_bf16 v[26:29], v[142:145], v[204:207], v[26:29]
	v_mfma_f32_16x16x32_bf16 v[26:29], v[138:141], v[190:193], v[26:29]
	v_mfma_f32_16x16x32_bf16 v[10:13], v[138:141], v[208:211], v[10:13]
	v_mfma_f32_16x16x32_bf16 v[10:13], v[142:145], v[212:215], v[10:13]
	s_add_u32 s51, s51, 0x100
	v_mfma_f32_16x16x32_bf16 v[14:17], v[134:137], v[212:215], v[14:17]
	v_mfma_f32_16x16x32_bf16 v[14:17], v[130:133], v[208:211], v[14:17]
	s_addc_u32 s70, s70, 0
	v_mfma_f32_16x16x32_bf16 v[54:57], v[146:149], v[162:165], v[54:57]
	v_mfma_f32_16x16x32_bf16 v[54:57], v[150:153], v[166:169], v[54:57]
	s_cmp_ge_i32 s71, s35
	v_mfma_f32_16x16x32_bf16 v[50:53], v[158:161], v[166:169], v[50:53]
	v_mfma_f32_16x16x32_bf16 v[50:53], v[154:157], v[162:165], v[50:53]
	s_mov_b64 s[0:1], s[4:5]
	v_mfma_f32_16x16x32_bf16 v[34:37], v[154:157], v[182:185], v[34:37]
	v_mfma_f32_16x16x32_bf16 v[34:37], v[158:161], v[186:189], v[34:37]
	s_mov_b32 s38, s71
	v_mfma_f32_16x16x32_bf16 v[38:41], v[150:153], v[186:189], v[38:41]
	v_mfma_f32_16x16x32_bf16 v[38:41], v[146:149], v[182:185], v[38:41]
	v_mfma_f32_16x16x32_bf16 v[22:25], v[146:149], v[190:193], v[22:25]
	v_mfma_f32_16x16x32_bf16 v[22:25], v[150:153], v[204:207], v[22:25]
	v_mfma_f32_16x16x32_bf16 v[18:21], v[158:161], v[204:207], v[18:21]
	v_mfma_f32_16x16x32_bf16 v[18:21], v[154:157], v[190:193], v[18:21]
	v_mfma_f32_16x16x32_bf16 v[2:5], v[154:157], v[208:211], v[2:5]
	v_mfma_f32_16x16x32_bf16 v[2:5], v[158:161], v[212:215], v[2:5]
	v_mfma_f32_16x16x32_bf16 v[6:9], v[150:153], v[212:215], v[6:9]
	v_mfma_f32_16x16x32_bf16 v[6:9], v[146:149], v[208:211], v[6:9]
	s_setprio 0
	s_barrier
	s_cbranch_scc0 .LBB0_305
	s_movk_i32 s51, 0x2000
	s_mov_b32 s73, 0x10000
	s_mov_b32 s75, 0x12000
	s_and_b64 vcc, exec, s[16:17]
	s_cbranch_vccz .LBB0_308

.LBB0_530:
	s_add_u32 vcc_lo, s14, 0xfff80000
	s_addc_u32 vcc_hi, s15, -1
	s_mov_b32 m0, s27
	s_nop 0
	global_load_lds_dwordx4 v138, vcc
	s_mov_b32 m0, s28
	s_nop 0
	global_load_lds_dwordx4 v140, vcc
	ds_read_b128 v[152:155], v145
	ds_read_b128 v[156:159], v145 offset:1024
	ds_read_b128 v[160:163], v145 offset:2048
	ds_read_b128 v[164:167], v145 offset:3072
	ds_read_b128 v[168:171], v145 offset:16384
	ds_read_b128 v[172:175], v145 offset:17408
	ds_read_b128 v[176:179], v145 offset:18432
	ds_read_b128 v[180:183], v145 offset:19456
	ds_read_b128 v[184:187], v151
	ds_read_b128 v[188:191], v151 offset:1024
	ds_read_b128 v[204:207], v151 offset:2048
	ds_read_b128 v[208:211], v151 offset:3072
	ds_read_b128 v[212:215], v151 offset:4096
	ds_read_b128 v[216:219], v151 offset:5120
	ds_read_b128 v[220:223], v151 offset:6144
	ds_read_b128 v[224:227], v151 offset:7168
	s_add_u32 s16, s14, 0xfff80080
	s_addc_u32 s17, s15, -1
	s_add_i32 s40, 0, 0x10000
	s_cmp_eq_u32 s39, 28
	s_cselect_b32 s19, s34, s17
	s_cselect_b32 s18, s35, s16
	s_cselect_b32 s17, s9, s38
	s_cselect_b32 s16, s36, s37
	s_add_i32 s42, 0, 0x14000
	s_add_i32 m0, s23, 0xc000
	s_nop 0
	global_load_lds_dwordx4 v138, s[14:15]
	s_add_i32 m0, s23, 0xe000
	s_nop 0
	global_load_lds_dwordx4 v140, s[14:15]
	s_waitcnt vmcnt(8)
	s_waitcnt lgkmcnt(0)
	v_mfma_f32_16x16x32_bf16 v[126:129], v[152:155], v[184:187], v[126:129]
	v_mfma_f32_16x16x32_bf16 v[126:129], v[156:159], v[188:191], v[126:129]
	v_mfma_f32_16x16x32_bf16 v[122:125], v[164:167], v[188:191], v[122:125]
	v_mfma_f32_16x16x32_bf16 v[122:125], v[160:163], v[184:187], v[122:125]
	s_barrier
	s_setprio 1
	v_mfma_f32_16x16x32_bf16 v[106:109], v[160:163], v[204:207], v[106:109]
	v_mfma_f32_16x16x32_bf16 v[106:109], v[164:167], v[208:211], v[106:109]
	v_mfma_f32_16x16x32_bf16 v[110:113], v[156:159], v[208:211], v[110:113]
	v_mfma_f32_16x16x32_bf16 v[110:113], v[152:155], v[204:207], v[110:113]
	v_mfma_f32_16x16x32_bf16 v[94:97], v[152:155], v[212:215], v[94:97]
	v_mfma_f32_16x16x32_bf16 v[94:97], v[156:159], v[216:219], v[94:97]
	v_mfma_f32_16x16x32_bf16 v[90:93], v[164:167], v[216:219], v[90:93]
	v_mfma_f32_16x16x32_bf16 v[90:93], v[160:163], v[212:215], v[90:93]
	v_mfma_f32_16x16x32_bf16 v[74:77], v[160:163], v[220:223], v[74:77]
	v_mfma_f32_16x16x32_bf16 v[74:77], v[164:167], v[224:227], v[74:77]
	v_mfma_f32_16x16x32_bf16 v[78:81], v[156:159], v[224:227], v[78:81]
	v_mfma_f32_16x16x32_bf16 v[78:81], v[152:155], v[220:223], v[78:81]
	v_mfma_f32_16x16x32_bf16 v[118:121], v[168:171], v[184:187], v[118:121]
	v_mfma_f32_16x16x32_bf16 v[118:121], v[172:175], v[188:191], v[118:121]
	v_mfma_f32_16x16x32_bf16 v[114:117], v[180:183], v[188:191], v[114:117]
	v_mfma_f32_16x16x32_bf16 v[114:117], v[176:179], v[184:187], v[114:117]
	v_mfma_f32_16x16x32_bf16 v[98:101], v[176:179], v[204:207], v[98:101]
	v_mfma_f32_16x16x32_bf16 v[98:101], v[180:183], v[208:211], v[98:101]
	v_mfma_f32_16x16x32_bf16 v[102:105], v[172:175], v[208:211], v[102:105]
	v_mfma_f32_16x16x32_bf16 v[102:105], v[168:171], v[204:207], v[102:105]
	v_mfma_f32_16x16x32_bf16 v[86:89], v[168:171], v[212:215], v[86:89]
	v_mfma_f32_16x16x32_bf16 v[86:89], v[172:175], v[216:219], v[86:89]
	v_mfma_f32_16x16x32_bf16 v[82:85], v[180:183], v[216:219], v[82:85]
	v_mfma_f32_16x16x32_bf16 v[82:85], v[176:179], v[212:215], v[82:85]
	v_mfma_f32_16x16x32_bf16 v[66:69], v[176:179], v[220:223], v[66:69]
	v_mfma_f32_16x16x32_bf16 v[66:69], v[180:183], v[224:227], v[66:69]
	v_mfma_f32_16x16x32_bf16 v[70:73], v[172:175], v[224:227], v[70:73]
	v_mfma_f32_16x16x32_bf16 v[70:73], v[168:171], v[220:223], v[70:73]
	s_setprio 0
	s_barrier
	ds_read_b128 v[184:187], v151 offset:16384
	ds_read_b128 v[188:191], v151 offset:17408
	ds_read_b128 v[204:207], v151 offset:18432
	ds_read_b128 v[208:211], v151 offset:19456
	ds_read_b128 v[212:215], v151 offset:20480
	ds_read_b128 v[216:219], v151 offset:21504
	ds_read_b128 v[220:223], v151 offset:22528
	ds_read_b128 v[224:227], v151 offset:23552
	s_add_i32 s40, s40, s22
	s_mov_b32 m0, s40
	s_nop 0
	global_load_lds_dwordx4 v134, s[16:17]
	s_add_i32 m0, s40, 0x2000
	s_add_u32 s40, s16, 0x80000
	s_addc_u32 s41, s17, 0
	s_add_i32 s42, s42, s22
	global_load_lds_dwordx4 v130, s[16:17]
	s_mov_b32 m0, s42
	s_nop 0
	global_load_lds_dwordx4 v134, s[40:41]
	s_add_i32 m0, s42, 0x2000
	s_nop 0
	global_load_lds_dwordx4 v130, s[40:41]
	s_waitcnt vmcnt(6)
	s_waitcnt lgkmcnt(0)
	v_mfma_f32_16x16x32_bf16 v[62:65], v[152:155], v[184:187], v[62:65]
	v_mfma_f32_16x16x32_bf16 v[62:65], v[156:159], v[188:191], v[62:65]
	v_mfma_f32_16x16x32_bf16 v[58:61], v[164:167], v[188:191], v[58:61]
	v_mfma_f32_16x16x32_bf16 v[58:61], v[160:163], v[184:187], v[58:61]
	s_barrier
	s_setprio 1
	v_mfma_f32_16x16x32_bf16 v[42:45], v[160:163], v[204:207], v[42:45]
	v_mfma_f32_16x16x32_bf16 v[42:45], v[164:167], v[208:211], v[42:45]
	v_mfma_f32_16x16x32_bf16 v[46:49], v[156:159], v[208:211], v[46:49]
	v_mfma_f32_16x16x32_bf16 v[46:49], v[152:155], v[204:207], v[46:49]
	v_mfma_f32_16x16x32_bf16 v[30:33], v[152:155], v[212:215], v[30:33]
	v_mfma_f32_16x16x32_bf16 v[30:33], v[156:159], v[216:219], v[30:33]
	v_mfma_f32_16x16x32_bf16 v[26:29], v[164:167], v[216:219], v[26:29]
	v_mfma_f32_16x16x32_bf16 v[26:29], v[160:163], v[212:215], v[26:29]
	v_mfma_f32_16x16x32_bf16 v[10:13], v[160:163], v[220:223], v[10:13]
	v_mfma_f32_16x16x32_bf16 v[10:13], v[164:167], v[224:227], v[10:13]
	v_mfma_f32_16x16x32_bf16 v[14:17], v[156:159], v[224:227], v[14:17]
	v_mfma_f32_16x16x32_bf16 v[14:17], v[152:155], v[220:223], v[14:17]
	v_mfma_f32_16x16x32_bf16 v[54:57], v[168:171], v[184:187], v[54:57]
	v_mfma_f32_16x16x32_bf16 v[54:57], v[172:175], v[188:191], v[54:57]
	v_mfma_f32_16x16x32_bf16 v[50:53], v[180:183], v[188:191], v[50:53]
	v_mfma_f32_16x16x32_bf16 v[50:53], v[176:179], v[184:187], v[50:53]
	v_mfma_f32_16x16x32_bf16 v[34:37], v[176:179], v[204:207], v[34:37]
	v_mfma_f32_16x16x32_bf16 v[34:37], v[180:183], v[208:211], v[34:37]
	v_mfma_f32_16x16x32_bf16 v[38:41], v[172:175], v[208:211], v[38:41]
	v_mfma_f32_16x16x32_bf16 v[38:41], v[168:171], v[204:207], v[38:41]
	v_mfma_f32_16x16x32_bf16 v[22:25], v[168:171], v[212:215], v[22:25]
	v_mfma_f32_16x16x32_bf16 v[22:25], v[172:175], v[216:219], v[22:25]
	v_mfma_f32_16x16x32_bf16 v[18:21], v[180:183], v[216:219], v[18:21]
	v_mfma_f32_16x16x32_bf16 v[18:21], v[176:179], v[212:215], v[18:21]
	v_mfma_f32_16x16x32_bf16 v[2:5], v[176:179], v[220:223], v[2:5]
	v_mfma_f32_16x16x32_bf16 v[2:5], v[180:183], v[224:227], v[2:5]
	v_mfma_f32_16x16x32_bf16 v[6:9], v[172:175], v[224:227], v[6:9]
	v_mfma_f32_16x16x32_bf16 v[6:9], v[168:171], v[220:223], v[6:9]
	s_setprio 0
	s_barrier
	s_mov_b32 m0, s23
	s_nop 0
	global_load_lds_dwordx4 v136, s[18:19]
	s_mov_b32 m0, s24
	s_nop 0
	global_load_lds_dwordx4 v132, s[18:19]
	ds_read_b128 v[152:155], v145 offset:32768
	ds_read_b128 v[156:159], v145 offset:33792
	ds_read_b128 v[160:163], v145 offset:34816
	ds_read_b128 v[164:167], v145 offset:35840
	ds_read_b128 v[168:171], v145 offset:49152
	ds_read_b128 v[172:175], v145 offset:50176
	ds_read_b128 v[176:179], v145 offset:51200
	ds_read_b128 v[180:183], v145 offset:52224
	ds_read_b128 v[184:187], v151 offset:32768
	ds_read_b128 v[188:191], v151 offset:33792
	ds_read_b128 v[204:207], v151 offset:34816
	ds_read_b128 v[208:211], v151 offset:35840
	ds_read_b128 v[212:215], v151 offset:36864
	ds_read_b128 v[216:219], v151 offset:37888
	ds_read_b128 v[220:223], v151 offset:38912
	ds_read_b128 v[224:227], v151 offset:39936
	s_add_i32 s40, 0, 0x18000
	s_add_i32 s41, 0, 0x1c000
	s_add_u32 s18, s18, 0x80000
	s_addc_u32 s19, s19, 0
	s_mov_b32 m0, s25
	s_nop 0
	global_load_lds_dwordx4 v136, s[18:19]
	s_mov_b32 m0, s26
	s_nop 0
	global_load_lds_dwordx4 v132, s[18:19]
	s_waitcnt vmcnt(8)
	s_waitcnt lgkmcnt(0)
	v_mfma_f32_16x16x32_bf16 v[126:129], v[152:155], v[184:187], v[126:129]
	v_mfma_f32_16x16x32_bf16 v[126:129], v[156:159], v[188:191], v[126:129]
	v_mfma_f32_16x16x32_bf16 v[122:125], v[164:167], v[188:191], v[122:125]
	v_mfma_f32_16x16x32_bf16 v[122:125], v[160:163], v[184:187], v[122:125]
	s_barrier
	s_setprio 1
	v_mfma_f32_16x16x32_bf16 v[106:109], v[160:163], v[204:207], v[106:109]
	v_mfma_f32_16x16x32_bf16 v[106:109], v[164:167], v[208:211], v[106:109]
	v_mfma_f32_16x16x32_bf16 v[110:113], v[156:159], v[208:211], v[110:113]
	v_mfma_f32_16x16x32_bf16 v[110:113], v[152:155], v[204:207], v[110:113]
	v_mfma_f32_16x16x32_bf16 v[94:97], v[152:155], v[212:215], v[94:97]
	v_mfma_f32_16x16x32_bf16 v[94:97], v[156:159], v[216:219], v[94:97]
	v_mfma_f32_16x16x32_bf16 v[90:93], v[164:167], v[216:219], v[90:93]
	v_mfma_f32_16x16x32_bf16 v[90:93], v[160:163], v[212:215], v[90:93]
	v_mfma_f32_16x16x32_bf16 v[74:77], v[160:163], v[220:223], v[74:77]
	v_mfma_f32_16x16x32_bf16 v[74:77], v[164:167], v[224:227], v[74:77]
	v_mfma_f32_16x16x32_bf16 v[78:81], v[156:159], v[224:227], v[78:81]
	v_mfma_f32_16x16x32_bf16 v[78:81], v[152:155], v[220:223], v[78:81]
	v_mfma_f32_16x16x32_bf16 v[118:121], v[168:171], v[184:187], v[118:121]
	v_mfma_f32_16x16x32_bf16 v[118:121], v[172:175], v[188:191], v[118:121]
	v_mfma_f32_16x16x32_bf16 v[114:117], v[180:183], v[188:191], v[114:117]
	v_mfma_f32_16x16x32_bf16 v[114:117], v[176:179], v[184:187], v[114:117]
	v_mfma_f32_16x16x32_bf16 v[98:101], v[176:179], v[204:207], v[98:101]
	v_mfma_f32_16x16x32_bf16 v[98:101], v[180:183], v[208:211], v[98:101]
	v_mfma_f32_16x16x32_bf16 v[102:105], v[172:175], v[208:211], v[102:105]
	v_mfma_f32_16x16x32_bf16 v[102:105], v[168:171], v[204:207], v[102:105]
	v_mfma_f32_16x16x32_bf16 v[86:89], v[168:171], v[212:215], v[86:89]
	v_mfma_f32_16x16x32_bf16 v[86:89], v[172:175], v[216:219], v[86:89]
	v_mfma_f32_16x16x32_bf16 v[82:85], v[180:183], v[216:219], v[82:85]
	v_mfma_f32_16x16x32_bf16 v[82:85], v[176:179], v[212:215], v[82:85]
	v_mfma_f32_16x16x32_bf16 v[66:69], v[176:179], v[220:223], v[66:69]
	v_mfma_f32_16x16x32_bf16 v[66:69], v[180:183], v[224:227], v[66:69]
	v_mfma_f32_16x16x32_bf16 v[70:73], v[172:175], v[224:227], v[70:73]
	v_mfma_f32_16x16x32_bf16 v[70:73], v[168:171], v[220:223], v[70:73]
	s_setprio 0
	s_barrier
	ds_read_b128 v[184:187], v151 offset:49152
	ds_read_b128 v[188:191], v151 offset:50176
	ds_read_b128 v[204:207], v151 offset:51200
	ds_read_b128 v[208:211], v151 offset:52224
	ds_read_b128 v[212:215], v151 offset:53248
	ds_read_b128 v[216:219], v151 offset:54272
	ds_read_b128 v[220:223], v151 offset:55296
	ds_read_b128 v[224:227], v151 offset:56320
	s_add_i32 s18, s40, s22
	s_add_u32 vcc_lo, s16, s94
	s_addc_u32 vcc_hi, s17, s95
	s_mov_b32 m0, s18
	s_nop 0
	global_load_lds_dwordx4 v134, vcc
	s_add_i32 m0, s18, 0x2000
	s_add_u32 s16, s16, 0x80080
	s_addc_u32 s17, s17, 0
	s_add_i32 s18, s41, s22
	global_load_lds_dwordx4 v130, vcc
	s_mov_b32 m0, s18
	s_nop 0
	global_load_lds_dwordx4 v134, s[16:17]
	s_add_i32 m0, s18, 0x2000
	s_nop 0
	global_load_lds_dwordx4 v130, s[16:17]
	s_waitcnt vmcnt(6)
	s_waitcnt lgkmcnt(0)
	v_mfma_f32_16x16x32_bf16 v[62:65], v[152:155], v[184:187], v[62:65]
	v_mfma_f32_16x16x32_bf16 v[62:65], v[156:159], v[188:191], v[62:65]
	v_mfma_f32_16x16x32_bf16 v[58:61], v[164:167], v[188:191], v[58:61]
	v_mfma_f32_16x16x32_bf16 v[58:61], v[160:163], v[184:187], v[58:61]
	s_barrier
	s_setprio 1
	v_mfma_f32_16x16x32_bf16 v[42:45], v[160:163], v[204:207], v[42:45]
	v_mfma_f32_16x16x32_bf16 v[42:45], v[164:167], v[208:211], v[42:45]
	v_mfma_f32_16x16x32_bf16 v[46:49], v[156:159], v[208:211], v[46:49]
	v_mfma_f32_16x16x32_bf16 v[46:49], v[152:155], v[204:207], v[46:49]
	v_mfma_f32_16x16x32_bf16 v[30:33], v[152:155], v[212:215], v[30:33]
	v_mfma_f32_16x16x32_bf16 v[30:33], v[156:159], v[216:219], v[30:33]
	v_mfma_f32_16x16x32_bf16 v[26:29], v[164:167], v[216:219], v[26:29]
	v_mfma_f32_16x16x32_bf16 v[26:29], v[160:163], v[212:215], v[26:29]
	v_mfma_f32_16x16x32_bf16 v[10:13], v[160:163], v[220:223], v[10:13]
	v_mfma_f32_16x16x32_bf16 v[10:13], v[164:167], v[224:227], v[10:13]
	s_add_i32 s39, s39, 2
	v_mfma_f32_16x16x32_bf16 v[14:17], v[156:159], v[224:227], v[14:17]
	v_mfma_f32_16x16x32_bf16 v[14:17], v[152:155], v[220:223], v[14:17]
	s_add_u32 s14, s14, 0x100
	v_mfma_f32_16x16x32_bf16 v[54:57], v[168:171], v[184:187], v[54:57]
	v_mfma_f32_16x16x32_bf16 v[54:57], v[172:175], v[188:191], v[54:57]
	s_addc_u32 s15, s15, 0
	v_mfma_f32_16x16x32_bf16 v[50:53], v[180:183], v[188:191], v[50:53]
	v_mfma_f32_16x16x32_bf16 v[50:53], v[176:179], v[184:187], v[50:53]
	s_add_u32 s37, s37, 0x100
	v_mfma_f32_16x16x32_bf16 v[34:37], v[176:179], v[204:207], v[34:37]
	v_mfma_f32_16x16x32_bf16 v[34:37], v[180:183], v[208:211], v[34:37]
	s_addc_u32 s38, s38, 0
	v_mfma_f32_16x16x32_bf16 v[38:41], v[172:175], v[208:211], v[38:41]
	v_mfma_f32_16x16x32_bf16 v[38:41], v[168:171], v[204:207], v[38:41]
	s_cmp_gt_u32 s39, 29
	v_mfma_f32_16x16x32_bf16 v[22:25], v[168:171], v[212:215], v[22:25]
	v_mfma_f32_16x16x32_bf16 v[22:25], v[172:175], v[216:219], v[22:25]
	v_mfma_f32_16x16x32_bf16 v[18:21], v[180:183], v[216:219], v[18:21]
	v_mfma_f32_16x16x32_bf16 v[18:21], v[176:179], v[212:215], v[18:21]
	v_mfma_f32_16x16x32_bf16 v[2:5], v[176:179], v[220:223], v[2:5]
	v_mfma_f32_16x16x32_bf16 v[2:5], v[180:183], v[224:227], v[2:5]
	v_mfma_f32_16x16x32_bf16 v[6:9], v[172:175], v[224:227], v[6:9]
	v_mfma_f32_16x16x32_bf16 v[6:9], v[168:171], v[220:223], v[6:9]
	s_setprio 0
	s_barrier
	s_cbranch_scc0 .LBB0_530

.LBB0_769:
	s_sub_u32 vcc_lo, s22, s12
	s_subb_u32 vcc_hi, s23, 0
	s_mov_b32 m0, s37
	s_nop 0
	global_load_lds_dwordx4 v214, vcc
	s_mov_b32 m0, s38
	s_nop 0
	global_load_lds_dwordx4 v212, vcc
	ds_read_b128 v[132:135], v231
	ds_read_b128 v[136:139], v231 offset:1024
	ds_read_b128 v[140:143], v231 offset:2048
	ds_read_b128 v[144:147], v231 offset:3072
	ds_read_b128 v[148:151], v231 offset:16384
	ds_read_b128 v[152:155], v231 offset:17408
	ds_read_b128 v[156:159], v231 offset:18432
	ds_read_b128 v[160:163], v231 offset:19456
	ds_read_b128 v[164:167], v197
	ds_read_b128 v[168:171], v197 offset:1024
	ds_read_b128 v[172:175], v197 offset:2048
	ds_read_b128 v[176:179], v197 offset:3072
	ds_read_b128 v[180:183], v197 offset:4096
	ds_read_b128 v[184:187], v197 offset:5120
	ds_read_b128 v[188:191], v197 offset:6144
	ds_read_b128 v[216:219], v197 offset:7168
	s_add_u32 s24, s22, 0x80
	s_addc_u32 s25, s23, 0
	s_add_i32 s57, 0, 0x10000
	s_cmp_eq_u32 s53, s56
	s_cselect_b32 s25, s1, s25
	s_cselect_b32 s24, s0, s24
	s_cselect_b32 s59, s19, s55
	s_cselect_b32 s58, s18, s54
	s_add_i32 s60, 0, 0x14000
	s_add_i32 m0, s33, 0xc000
	s_nop 0
	global_load_lds_dwordx4 v214, s[22:23]
	s_add_i32 m0, s33, 0xe000
	s_nop 0
	global_load_lds_dwordx4 v212, s[22:23]
	s_waitcnt vmcnt(8)
	s_waitcnt lgkmcnt(0)
	v_mfma_f32_16x16x32_bf16 v[126:129], v[132:135], v[164:167], v[126:129]
	v_mfma_f32_16x16x32_bf16 v[126:129], v[136:139], v[168:171], v[126:129]
	v_mfma_f32_16x16x32_bf16 v[122:125], v[144:147], v[168:171], v[122:125]
	v_mfma_f32_16x16x32_bf16 v[122:125], v[140:143], v[164:167], v[122:125]
	s_barrier
	s_setprio 1
	v_mfma_f32_16x16x32_bf16 v[106:109], v[140:143], v[172:175], v[106:109]
	v_mfma_f32_16x16x32_bf16 v[106:109], v[144:147], v[176:179], v[106:109]
	v_mfma_f32_16x16x32_bf16 v[110:113], v[136:139], v[176:179], v[110:113]
	v_mfma_f32_16x16x32_bf16 v[110:113], v[132:135], v[172:175], v[110:113]
	v_mfma_f32_16x16x32_bf16 v[94:97], v[132:135], v[180:183], v[94:97]
	v_mfma_f32_16x16x32_bf16 v[94:97], v[136:139], v[184:187], v[94:97]
	v_mfma_f32_16x16x32_bf16 v[90:93], v[144:147], v[184:187], v[90:93]
	v_mfma_f32_16x16x32_bf16 v[90:93], v[140:143], v[180:183], v[90:93]
	v_mfma_f32_16x16x32_bf16 v[74:77], v[140:143], v[188:191], v[74:77]
	v_mfma_f32_16x16x32_bf16 v[74:77], v[144:147], v[216:219], v[74:77]
	v_mfma_f32_16x16x32_bf16 v[78:81], v[136:139], v[216:219], v[78:81]
	v_mfma_f32_16x16x32_bf16 v[78:81], v[132:135], v[188:191], v[78:81]
	v_mfma_f32_16x16x32_bf16 v[118:121], v[148:151], v[164:167], v[118:121]
	v_mfma_f32_16x16x32_bf16 v[118:121], v[152:155], v[168:171], v[118:121]
	v_mfma_f32_16x16x32_bf16 v[114:117], v[160:163], v[168:171], v[114:117]
	v_mfma_f32_16x16x32_bf16 v[114:117], v[156:159], v[164:167], v[114:117]
	v_mfma_f32_16x16x32_bf16 v[98:101], v[156:159], v[172:175], v[98:101]
	v_mfma_f32_16x16x32_bf16 v[98:101], v[160:163], v[176:179], v[98:101]
	v_mfma_f32_16x16x32_bf16 v[102:105], v[152:155], v[176:179], v[102:105]
	v_mfma_f32_16x16x32_bf16 v[102:105], v[148:151], v[172:175], v[102:105]
	v_mfma_f32_16x16x32_bf16 v[86:89], v[148:151], v[180:183], v[86:89]
	v_mfma_f32_16x16x32_bf16 v[86:89], v[152:155], v[184:187], v[86:89]
	v_mfma_f32_16x16x32_bf16 v[82:85], v[160:163], v[184:187], v[82:85]
	v_mfma_f32_16x16x32_bf16 v[82:85], v[156:159], v[180:183], v[82:85]
	v_mfma_f32_16x16x32_bf16 v[66:69], v[156:159], v[188:191], v[66:69]
	v_mfma_f32_16x16x32_bf16 v[66:69], v[160:163], v[216:219], v[66:69]
	v_mfma_f32_16x16x32_bf16 v[70:73], v[152:155], v[216:219], v[70:73]
	v_mfma_f32_16x16x32_bf16 v[70:73], v[148:151], v[188:191], v[70:73]
	s_setprio 0
	s_barrier
	ds_read_b128 v[164:167], v197 offset:16384
	ds_read_b128 v[168:171], v197 offset:17408
	ds_read_b128 v[172:175], v197 offset:18432
	ds_read_b128 v[176:179], v197 offset:19456
	ds_read_b128 v[180:183], v197 offset:20480
	ds_read_b128 v[184:187], v197 offset:21504
	ds_read_b128 v[188:191], v197 offset:22528
	ds_read_b128 v[216:219], v197 offset:23552
	s_add_i32 s57, s57, s26
	v_lshl_add_u64 v[192:193], s[58:59], 0, v[208:209]
	s_mov_b32 m0, s57
	s_nop 0
	global_load_lds_dwordx4 v208, s[58:59]
	s_add_i32 m0, s57, 0x2000
	v_lshl_add_u64 v[220:221], s[58:59], 0, v[204:205]
	s_add_u32 s58, s58, s12
	s_addc_u32 s59, s59, 0
	s_add_i32 s57, s60, s26
	global_load_lds_dwordx4 v[220:221], off
	v_lshl_add_u64 v[224:225], s[58:59], 0, v[208:209]
	s_mov_b32 m0, s57
	v_lshl_add_u64 v[226:227], s[58:59], 0, v[204:205]
	global_load_lds_dwordx4 v208, s[58:59]
	s_add_i32 m0, s57, 0x2000
	s_nop 0
	global_load_lds_dwordx4 v204, s[58:59]
	s_waitcnt vmcnt(6)
	s_waitcnt lgkmcnt(0)
	v_mfma_f32_16x16x32_bf16 v[62:65], v[132:135], v[164:167], v[62:65]
	v_mfma_f32_16x16x32_bf16 v[62:65], v[136:139], v[168:171], v[62:65]
	v_mfma_f32_16x16x32_bf16 v[58:61], v[144:147], v[168:171], v[58:61]
	v_mfma_f32_16x16x32_bf16 v[58:61], v[140:143], v[164:167], v[58:61]
	s_barrier
	s_setprio 1
	v_mfma_f32_16x16x32_bf16 v[42:45], v[140:143], v[172:175], v[42:45]
	v_mfma_f32_16x16x32_bf16 v[42:45], v[144:147], v[176:179], v[42:45]
	v_mfma_f32_16x16x32_bf16 v[46:49], v[136:139], v[176:179], v[46:49]
	v_mfma_f32_16x16x32_bf16 v[46:49], v[132:135], v[172:175], v[46:49]
	v_mfma_f32_16x16x32_bf16 v[30:33], v[132:135], v[180:183], v[30:33]
	v_mfma_f32_16x16x32_bf16 v[30:33], v[136:139], v[184:187], v[30:33]
	v_mfma_f32_16x16x32_bf16 v[26:29], v[144:147], v[184:187], v[26:29]
	v_mfma_f32_16x16x32_bf16 v[26:29], v[140:143], v[180:183], v[26:29]
	v_mfma_f32_16x16x32_bf16 v[10:13], v[140:143], v[188:191], v[10:13]
	v_mfma_f32_16x16x32_bf16 v[10:13], v[144:147], v[216:219], v[10:13]
	v_mfma_f32_16x16x32_bf16 v[14:17], v[136:139], v[216:219], v[14:17]
	v_mfma_f32_16x16x32_bf16 v[14:17], v[132:135], v[188:191], v[14:17]
	v_mfma_f32_16x16x32_bf16 v[54:57], v[148:151], v[164:167], v[54:57]
	v_mfma_f32_16x16x32_bf16 v[54:57], v[152:155], v[168:171], v[54:57]
	v_mfma_f32_16x16x32_bf16 v[50:53], v[160:163], v[168:171], v[50:53]
	v_mfma_f32_16x16x32_bf16 v[50:53], v[156:159], v[164:167], v[50:53]
	v_mfma_f32_16x16x32_bf16 v[34:37], v[156:159], v[172:175], v[34:37]
	v_mfma_f32_16x16x32_bf16 v[34:37], v[160:163], v[176:179], v[34:37]
	v_mfma_f32_16x16x32_bf16 v[38:41], v[152:155], v[176:179], v[38:41]
	v_mfma_f32_16x16x32_bf16 v[38:41], v[148:151], v[172:175], v[38:41]
	v_mfma_f32_16x16x32_bf16 v[22:25], v[148:151], v[180:183], v[22:25]
	v_mfma_f32_16x16x32_bf16 v[22:25], v[152:155], v[184:187], v[22:25]
	v_mfma_f32_16x16x32_bf16 v[18:21], v[160:163], v[184:187], v[18:21]
	v_mfma_f32_16x16x32_bf16 v[18:21], v[156:159], v[180:183], v[18:21]
	v_mfma_f32_16x16x32_bf16 v[2:5], v[156:159], v[188:191], v[2:5]
	v_mfma_f32_16x16x32_bf16 v[2:5], v[160:163], v[216:219], v[2:5]
	v_mfma_f32_16x16x32_bf16 v[6:9], v[152:155], v[216:219], v[6:9]
	v_mfma_f32_16x16x32_bf16 v[6:9], v[148:151], v[188:191], v[6:9]
	s_setprio 0
	s_barrier
	s_mov_b32 m0, s33
	s_nop 0
	global_load_lds_dwordx4 v210, s[24:25]
	s_mov_b32 m0, s34
	s_nop 0
	global_load_lds_dwordx4 v206, s[24:25]
	ds_read_b128 v[132:135], v231 offset:32768
	ds_read_b128 v[136:139], v231 offset:33792
	ds_read_b128 v[140:143], v231 offset:34816
	ds_read_b128 v[144:147], v231 offset:35840
	ds_read_b128 v[148:151], v231 offset:49152
	ds_read_b128 v[152:155], v231 offset:50176
	ds_read_b128 v[156:159], v231 offset:51200
	ds_read_b128 v[160:163], v231 offset:52224
	ds_read_b128 v[164:167], v197 offset:32768
	ds_read_b128 v[168:171], v197 offset:33792
	ds_read_b128 v[172:175], v197 offset:34816
	ds_read_b128 v[176:179], v197 offset:35840
	ds_read_b128 v[180:183], v197 offset:36864
	ds_read_b128 v[184:187], v197 offset:37888
	ds_read_b128 v[188:191], v197 offset:38912
	ds_read_b128 v[216:219], v197 offset:39936
	s_add_i32 s57, 0, 0x18000
	s_add_i32 s58, 0, 0x1c000
	s_add_u32 s24, s24, s12
	s_addc_u32 s25, s25, 0
	s_mov_b32 m0, s35
	s_nop 0
	global_load_lds_dwordx4 v210, s[24:25]
	s_mov_b32 m0, s36
	s_nop 0
	global_load_lds_dwordx4 v206, s[24:25]
	s_waitcnt vmcnt(8)
	s_waitcnt lgkmcnt(0)
	v_mfma_f32_16x16x32_bf16 v[126:129], v[132:135], v[164:167], v[126:129]
	v_mfma_f32_16x16x32_bf16 v[126:129], v[136:139], v[168:171], v[126:129]
	v_mfma_f32_16x16x32_bf16 v[122:125], v[144:147], v[168:171], v[122:125]
	v_mfma_f32_16x16x32_bf16 v[122:125], v[140:143], v[164:167], v[122:125]
	s_barrier
	s_setprio 1
	v_mfma_f32_16x16x32_bf16 v[106:109], v[140:143], v[172:175], v[106:109]
	v_mfma_f32_16x16x32_bf16 v[106:109], v[144:147], v[176:179], v[106:109]
	v_mfma_f32_16x16x32_bf16 v[110:113], v[136:139], v[176:179], v[110:113]
	v_mfma_f32_16x16x32_bf16 v[110:113], v[132:135], v[172:175], v[110:113]
	v_mfma_f32_16x16x32_bf16 v[94:97], v[132:135], v[180:183], v[94:97]
	v_mfma_f32_16x16x32_bf16 v[94:97], v[136:139], v[184:187], v[94:97]
	v_mfma_f32_16x16x32_bf16 v[90:93], v[144:147], v[184:187], v[90:93]
	v_mfma_f32_16x16x32_bf16 v[90:93], v[140:143], v[180:183], v[90:93]
	v_mfma_f32_16x16x32_bf16 v[74:77], v[140:143], v[188:191], v[74:77]
	v_mfma_f32_16x16x32_bf16 v[74:77], v[144:147], v[216:219], v[74:77]
	v_mfma_f32_16x16x32_bf16 v[78:81], v[136:139], v[216:219], v[78:81]
	v_mfma_f32_16x16x32_bf16 v[78:81], v[132:135], v[188:191], v[78:81]
	v_mfma_f32_16x16x32_bf16 v[118:121], v[148:151], v[164:167], v[118:121]
	v_mfma_f32_16x16x32_bf16 v[118:121], v[152:155], v[168:171], v[118:121]
	v_mfma_f32_16x16x32_bf16 v[114:117], v[160:163], v[168:171], v[114:117]
	v_mfma_f32_16x16x32_bf16 v[114:117], v[156:159], v[164:167], v[114:117]
	v_mfma_f32_16x16x32_bf16 v[98:101], v[156:159], v[172:175], v[98:101]
	v_mfma_f32_16x16x32_bf16 v[98:101], v[160:163], v[176:179], v[98:101]
	v_mfma_f32_16x16x32_bf16 v[102:105], v[152:155], v[176:179], v[102:105]
	v_mfma_f32_16x16x32_bf16 v[102:105], v[148:151], v[172:175], v[102:105]
	v_mfma_f32_16x16x32_bf16 v[86:89], v[148:151], v[180:183], v[86:89]
	v_mfma_f32_16x16x32_bf16 v[86:89], v[152:155], v[184:187], v[86:89]
	v_mfma_f32_16x16x32_bf16 v[82:85], v[160:163], v[184:187], v[82:85]
	v_mfma_f32_16x16x32_bf16 v[82:85], v[156:159], v[180:183], v[82:85]
	v_mfma_f32_16x16x32_bf16 v[66:69], v[156:159], v[188:191], v[66:69]
	v_mfma_f32_16x16x32_bf16 v[66:69], v[160:163], v[216:219], v[66:69]
	v_mfma_f32_16x16x32_bf16 v[70:73], v[152:155], v[216:219], v[70:73]
	v_mfma_f32_16x16x32_bf16 v[70:73], v[148:151], v[188:191], v[70:73]
	s_setprio 0
	s_barrier
	ds_read_b128 v[164:167], v197 offset:49152
	ds_read_b128 v[168:171], v197 offset:50176
	ds_read_b128 v[172:175], v197 offset:51200
	ds_read_b128 v[176:179], v197 offset:52224
	ds_read_b128 v[180:183], v197 offset:53248
	ds_read_b128 v[184:187], v197 offset:54272
	ds_read_b128 v[188:191], v197 offset:55296
	ds_read_b128 v[216:219], v197 offset:56320
	s_add_i32 s24, s57, s26
	v_lshl_add_u64 v[192:193], v[192:193], 0, s[94:95]
	s_mov_b32 m0, s24
	s_nop 0
	global_load_lds_dwordx4 v[192:193], off
	v_lshl_add_u64 v[192:193], v[220:221], 0, s[94:95]
	s_add_i32 m0, s24, 0x2000
	s_add_i32 s24, s58, s26
	global_load_lds_dwordx4 v[192:193], off
	v_lshl_add_u64 v[192:193], v[224:225], 0, s[94:95]
	s_mov_b32 m0, s24
	s_nop 0
	global_load_lds_dwordx4 v[192:193], off
	v_lshl_add_u64 v[192:193], v[226:227], 0, s[94:95]
	s_add_i32 m0, s24, 0x2000
	s_nop 0
	global_load_lds_dwordx4 v[192:193], off
	s_waitcnt vmcnt(6)
	s_waitcnt lgkmcnt(0)
	v_mfma_f32_16x16x32_bf16 v[62:65], v[132:135], v[164:167], v[62:65]
	v_mfma_f32_16x16x32_bf16 v[62:65], v[136:139], v[168:171], v[62:65]
	v_mfma_f32_16x16x32_bf16 v[58:61], v[144:147], v[168:171], v[58:61]
	v_mfma_f32_16x16x32_bf16 v[58:61], v[140:143], v[164:167], v[58:61]
	s_barrier
	s_setprio 1
	v_mfma_f32_16x16x32_bf16 v[42:45], v[140:143], v[172:175], v[42:45]
	v_mfma_f32_16x16x32_bf16 v[42:45], v[144:147], v[176:179], v[42:45]
	v_mfma_f32_16x16x32_bf16 v[46:49], v[136:139], v[176:179], v[46:49]
	v_mfma_f32_16x16x32_bf16 v[46:49], v[132:135], v[172:175], v[46:49]
	v_mfma_f32_16x16x32_bf16 v[30:33], v[132:135], v[180:183], v[30:33]
	v_mfma_f32_16x16x32_bf16 v[30:33], v[136:139], v[184:187], v[30:33]
	v_mfma_f32_16x16x32_bf16 v[26:29], v[144:147], v[184:187], v[26:29]
	v_mfma_f32_16x16x32_bf16 v[26:29], v[140:143], v[180:183], v[26:29]
	v_mfma_f32_16x16x32_bf16 v[10:13], v[140:143], v[188:191], v[10:13]
	v_mfma_f32_16x16x32_bf16 v[10:13], v[144:147], v[216:219], v[10:13]
	v_mfma_f32_16x16x32_bf16 v[14:17], v[136:139], v[216:219], v[14:17]
	v_mfma_f32_16x16x32_bf16 v[14:17], v[132:135], v[188:191], v[14:17]
	v_mfma_f32_16x16x32_bf16 v[54:57], v[148:151], v[164:167], v[54:57]
	v_mfma_f32_16x16x32_bf16 v[54:57], v[152:155], v[168:171], v[54:57]
	v_mfma_f32_16x16x32_bf16 v[50:53], v[160:163], v[168:171], v[50:53]
	v_mfma_f32_16x16x32_bf16 v[50:53], v[156:159], v[164:167], v[50:53]
	v_mfma_f32_16x16x32_bf16 v[34:37], v[156:159], v[172:175], v[34:37]
	v_mfma_f32_16x16x32_bf16 v[34:37], v[160:163], v[176:179], v[34:37]
	v_mfma_f32_16x16x32_bf16 v[38:41], v[152:155], v[176:179], v[38:41]
	v_mfma_f32_16x16x32_bf16 v[38:41], v[148:151], v[172:175], v[38:41]
	v_mfma_f32_16x16x32_bf16 v[22:25], v[148:151], v[180:183], v[22:25]
	v_mfma_f32_16x16x32_bf16 v[22:25], v[152:155], v[184:187], v[22:25]
	v_mfma_f32_16x16x32_bf16 v[18:21], v[160:163], v[184:187], v[18:21]
	v_mfma_f32_16x16x32_bf16 v[18:21], v[156:159], v[180:183], v[18:21]
	v_mfma_f32_16x16x32_bf16 v[2:5], v[156:159], v[188:191], v[2:5]
	v_mfma_f32_16x16x32_bf16 v[2:5], v[160:163], v[216:219], v[2:5]
	v_mfma_f32_16x16x32_bf16 v[6:9], v[152:155], v[216:219], v[6:9]
	v_mfma_f32_16x16x32_bf16 v[6:9], v[148:151], v[188:191], v[6:9]
	s_setprio 0
	s_barrier
	s_and_b32 s24, s56, 6
	s_cmp_eq_u32 s24, 0
	s_cselect_b64 s[58:59], -1, 0
	s_cmp_ge_u32 s56, s53
	s_cselect_b64 s[24:25], -1, 0
	s_cmp_lt_u32 s56, s53
	s_cselect_b64 s[60:61], -1, 0
	s_and_b64 s[58:59], s[58:59], s[60:61]
	s_andn2_b64 vcc, exec, s[58:59]
	s_cbranch_vccnz .LBB0_768
	v_add_u32_e32 v131, 0x400, v130
	v_add_u32_e32 v148, 0x1000, v130
	v_add_u32_e32 v149, 0x1400, v130
	ds_read2_b32 v[132:133], v130 offset1:1
	ds_read2_b32 v[134:135], v130 offset0:128 offset1:129
	ds_read2_b32 v[136:137], v131 offset1:1
	ds_read2_b32 v[138:139], v131 offset0:128 offset1:129
	ds_read2_b32 v[140:141], v148 offset1:1
	ds_read2_b32 v[142:143], v148 offset0:128 offset1:129
	ds_read2_b32 v[144:145], v149 offset1:1
	ds_read2_b32 v[146:147], v149 offset0:128 offset1:129
	s_waitcnt lgkmcnt(0)
	v_rcp_f32_e32 v150, v133
	v_rcp_f32_e32 v151, v135
	v_rcp_f32_e32 v152, v137
	v_rcp_f32_e32 v153, v139
	v_rcp_f32_e32 v154, v141
	v_rcp_f32_e32 v155, v143
	v_rcp_f32_e32 v156, v145
	v_rcp_f32_e32 v157, v147
	v_mul_f32_e32 v132, v132, v150
	v_mul_f32_e32 v134, v134, v151
	v_mul_f32_e32 v136, v136, v152
	v_mul_f32_e32 v138, v138, v153
	v_mul_f32_e32 v140, v140, v154
	v_mul_f32_e32 v142, v142, v155
	v_mul_f32_e32 v144, v144, v156
	v_mul_f32_e32 v146, v146, v157
	v_pk_mul_f32 v[128:129], v[128:129], v[132:133] op_sel_hi:[1,0]
	v_pk_mul_f32 v[126:127], v[126:127], v[132:133] op_sel_hi:[1,0]
	v_pk_mul_f32 v[124:125], v[124:125], v[132:133] op_sel_hi:[1,0]
	v_pk_mul_f32 v[122:123], v[122:123], v[132:133] op_sel_hi:[1,0]
	v_pk_mul_f32 v[120:121], v[120:121], v[132:133] op_sel_hi:[1,0]
	v_pk_mul_f32 v[118:119], v[118:119], v[132:133] op_sel_hi:[1,0]
	v_pk_mul_f32 v[116:117], v[116:117], v[132:133] op_sel_hi:[1,0]
	v_pk_mul_f32 v[114:115], v[114:115], v[132:133] op_sel_hi:[1,0]
	v_pk_mul_f32 v[112:113], v[112:113], v[134:135] op_sel_hi:[1,0]
	v_pk_mul_f32 v[110:111], v[110:111], v[134:135] op_sel_hi:[1,0]
	v_pk_mul_f32 v[108:109], v[108:109], v[134:135] op_sel_hi:[1,0]
	v_pk_mul_f32 v[106:107], v[106:107], v[134:135] op_sel_hi:[1,0]
	v_pk_mul_f32 v[104:105], v[104:105], v[134:135] op_sel_hi:[1,0]
	v_pk_mul_f32 v[102:103], v[102:103], v[134:135] op_sel_hi:[1,0]
	v_pk_mul_f32 v[100:101], v[100:101], v[134:135] op_sel_hi:[1,0]
	v_pk_mul_f32 v[98:99], v[98:99], v[134:135] op_sel_hi:[1,0]
	v_pk_mul_f32 v[96:97], v[96:97], v[136:137] op_sel_hi:[1,0]
	v_pk_mul_f32 v[94:95], v[94:95], v[136:137] op_sel_hi:[1,0]
	v_pk_mul_f32 v[92:93], v[92:93], v[136:137] op_sel_hi:[1,0]
	v_pk_mul_f32 v[90:91], v[90:91], v[136:137] op_sel_hi:[1,0]
	v_pk_mul_f32 v[88:89], v[88:89], v[136:137] op_sel_hi:[1,0]
	v_pk_mul_f32 v[86:87], v[86:87], v[136:137] op_sel_hi:[1,0]
	v_pk_mul_f32 v[84:85], v[84:85], v[136:137] op_sel_hi:[1,0]
	v_pk_mul_f32 v[82:83], v[82:83], v[136:137] op_sel_hi:[1,0]
	v_pk_mul_f32 v[80:81], v[80:81], v[138:139] op_sel_hi:[1,0]
	v_pk_mul_f32 v[78:79], v[78:79], v[138:139] op_sel_hi:[1,0]
	v_pk_mul_f32 v[76:77], v[76:77], v[138:139] op_sel_hi:[1,0]
	v_pk_mul_f32 v[74:75], v[74:75], v[138:139] op_sel_hi:[1,0]
	v_pk_mul_f32 v[72:73], v[72:73], v[138:139] op_sel_hi:[1,0]
	v_pk_mul_f32 v[70:71], v[70:71], v[138:139] op_sel_hi:[1,0]
	v_pk_mul_f32 v[68:69], v[68:69], v[138:139] op_sel_hi:[1,0]
	v_pk_mul_f32 v[66:67], v[66:67], v[138:139] op_sel_hi:[1,0]
	v_pk_mul_f32 v[64:65], v[64:65], v[140:141] op_sel_hi:[1,0]
	v_pk_mul_f32 v[62:63], v[62:63], v[140:141] op_sel_hi:[1,0]
	v_pk_mul_f32 v[60:61], v[60:61], v[140:141] op_sel_hi:[1,0]
	v_pk_mul_f32 v[58:59], v[58:59], v[140:141] op_sel_hi:[1,0]
	v_pk_mul_f32 v[56:57], v[56:57], v[140:141] op_sel_hi:[1,0]
	v_pk_mul_f32 v[54:55], v[54:55], v[140:141] op_sel_hi:[1,0]
	v_pk_mul_f32 v[52:53], v[52:53], v[140:141] op_sel_hi:[1,0]
	v_pk_mul_f32 v[50:51], v[50:51], v[140:141] op_sel_hi:[1,0]
	v_pk_mul_f32 v[48:49], v[48:49], v[142:143] op_sel_hi:[1,0]
	v_pk_mul_f32 v[46:47], v[46:47], v[142:143] op_sel_hi:[1,0]
	v_pk_mul_f32 v[44:45], v[44:45], v[142:143] op_sel_hi:[1,0]
	v_pk_mul_f32 v[42:43], v[42:43], v[142:143] op_sel_hi:[1,0]
	v_pk_mul_f32 v[40:41], v[40:41], v[142:143] op_sel_hi:[1,0]
	v_pk_mul_f32 v[38:39], v[38:39], v[142:143] op_sel_hi:[1,0]
	v_pk_mul_f32 v[36:37], v[36:37], v[142:143] op_sel_hi:[1,0]
	v_pk_mul_f32 v[34:35], v[34:35], v[142:143] op_sel_hi:[1,0]
	v_pk_mul_f32 v[32:33], v[32:33], v[144:145] op_sel_hi:[1,0]
	v_pk_mul_f32 v[30:31], v[30:31], v[144:145] op_sel_hi:[1,0]
	v_pk_mul_f32 v[28:29], v[28:29], v[144:145] op_sel_hi:[1,0]
	v_pk_mul_f32 v[26:27], v[26:27], v[144:145] op_sel_hi:[1,0]
	v_pk_mul_f32 v[24:25], v[24:25], v[144:145] op_sel_hi:[1,0]
	v_pk_mul_f32 v[22:23], v[22:23], v[144:145] op_sel_hi:[1,0]
	v_pk_mul_f32 v[20:21], v[20:21], v[144:145] op_sel_hi:[1,0]
	v_pk_mul_f32 v[18:19], v[18:19], v[144:145] op_sel_hi:[1,0]
	v_pk_mul_f32 v[16:17], v[16:17], v[146:147] op_sel_hi:[1,0]
	v_pk_mul_f32 v[14:15], v[14:15], v[146:147] op_sel_hi:[1,0]
	v_pk_mul_f32 v[12:13], v[12:13], v[146:147] op_sel_hi:[1,0]
	v_pk_mul_f32 v[10:11], v[10:11], v[146:147] op_sel_hi:[1,0]
	v_pk_mul_f32 v[8:9], v[8:9], v[146:147] op_sel_hi:[1,0]
	v_pk_mul_f32 v[6:7], v[6:7], v[146:147] op_sel_hi:[1,0]
	v_pk_mul_f32 v[4:5], v[4:5], v[146:147] op_sel_hi:[1,0]
	v_pk_mul_f32 v[2:3], v[2:3], v[146:147] op_sel_hi:[1,0]
	s_branch .LBB0_768

.LBB0_850:
	s_sub_u32 vcc_lo, s18, s12
	s_subb_u32 vcc_hi, s19, 0
	s_mov_b32 m0, s33
	s_nop 0
	global_load_lds_dwordx4 v210, vcc
	s_mov_b32 m0, s34
	s_nop 0
	global_load_lds_dwordx4 v212, vcc
	ds_read_b128 v[66:69], v198
	ds_read_b128 v[78:81], v198 offset:1024
	ds_read_b128 v[82:85], v198 offset:2048
	ds_read_b128 v[98:101], v198 offset:3072
	ds_read_b128 v[106:109], v198 offset:16384
	ds_read_b128 v[118:121], v198 offset:17408
	ds_read_b128 v[130:133], v198 offset:18432
	ds_read_b128 v[142:145], v198 offset:19456
	ds_read_b128 v[150:153], v234
	ds_read_b128 v[154:157], v234 offset:1024
	ds_read_b128 v[158:161], v234 offset:2048
	ds_read_b128 v[162:165], v234 offset:3072
	ds_read_b128 v[170:173], v234 offset:4096
	ds_read_b128 v[174:177], v234 offset:5120
	ds_read_b128 v[178:181], v234 offset:6144
	ds_read_b128 v[190:193], v234 offset:7168
	s_add_i32 s55, s20, 2
	s_add_u32 s56, s18, 0x80
	s_addc_u32 s21, s19, 0
	s_add_i32 s58, 0, 0x10000
	s_cmp_eq_u32 s35, s20
	s_cselect_b32 s21, s1, s21
	s_cselect_b32 s20, s0, s56
	s_cselect_b32 s57, s17, s54
	s_cselect_b32 s56, s16, s51
	s_add_i32 s59, 0, 0x14000
	s_add_i32 m0, s26, 0xc000
	s_nop 0
	global_load_lds_dwordx4 v210, s[18:19]
	s_add_i32 m0, s26, 0xe000
	s_nop 0
	global_load_lds_dwordx4 v212, s[18:19]
	s_waitcnt vmcnt(8)
	s_waitcnt lgkmcnt(0)
	v_mfma_f32_16x16x32_bf16 v[186:189], v[66:69], v[150:153], v[186:189]
	v_mfma_f32_16x16x32_bf16 v[186:189], v[78:81], v[154:157], v[186:189]
	v_mfma_f32_16x16x32_bf16 v[182:185], v[98:101], v[154:157], v[182:185]
	v_mfma_f32_16x16x32_bf16 v[182:185], v[82:85], v[150:153], v[182:185]
	s_barrier
	s_setprio 1
	v_mfma_f32_16x16x32_bf16 v[134:137], v[82:85], v[158:161], v[134:137]
	v_mfma_f32_16x16x32_bf16 v[134:137], v[98:101], v[162:165], v[134:137]
	v_mfma_f32_16x16x32_bf16 v[138:141], v[78:81], v[162:165], v[138:141]
	v_mfma_f32_16x16x32_bf16 v[138:141], v[66:69], v[158:161], v[138:141]
	v_mfma_f32_16x16x32_bf16 v[114:117], v[66:69], v[170:173], v[114:117]
	v_mfma_f32_16x16x32_bf16 v[114:117], v[78:81], v[174:177], v[114:117]
	v_mfma_f32_16x16x32_bf16 v[110:113], v[98:101], v[174:177], v[110:113]
	v_mfma_f32_16x16x32_bf16 v[110:113], v[82:85], v[170:173], v[110:113]
	v_mfma_f32_16x16x32_bf16 v[86:89], v[82:85], v[178:181], v[86:89]
	v_mfma_f32_16x16x32_bf16 v[86:89], v[98:101], v[190:193], v[86:89]
	v_mfma_f32_16x16x32_bf16 v[90:93], v[78:81], v[190:193], v[90:93]
	v_mfma_f32_16x16x32_bf16 v[90:93], v[66:69], v[178:181], v[90:93]
	v_mfma_f32_16x16x32_bf16 v[166:169], v[106:109], v[150:153], v[166:169]
	v_mfma_f32_16x16x32_bf16 v[166:169], v[118:121], v[154:157], v[166:169]
	v_mfma_f32_16x16x32_bf16 v[146:149], v[142:145], v[154:157], v[146:149]
	v_mfma_f32_16x16x32_bf16 v[146:149], v[130:133], v[150:153], v[146:149]
	v_mfma_f32_16x16x32_bf16 v[122:125], v[130:133], v[158:161], v[122:125]
	v_mfma_f32_16x16x32_bf16 v[122:125], v[142:145], v[162:165], v[122:125]
	v_mfma_f32_16x16x32_bf16 v[126:129], v[118:121], v[162:165], v[126:129]
	v_mfma_f32_16x16x32_bf16 v[126:129], v[106:109], v[158:161], v[126:129]
	v_mfma_f32_16x16x32_bf16 v[102:105], v[106:109], v[170:173], v[102:105]
	v_mfma_f32_16x16x32_bf16 v[102:105], v[118:121], v[174:177], v[102:105]
	v_mfma_f32_16x16x32_bf16 v[94:97], v[142:145], v[174:177], v[94:97]
	v_mfma_f32_16x16x32_bf16 v[94:97], v[130:133], v[170:173], v[94:97]
	v_mfma_f32_16x16x32_bf16 v[70:73], v[130:133], v[178:181], v[70:73]
	v_mfma_f32_16x16x32_bf16 v[70:73], v[142:145], v[190:193], v[70:73]
	v_mfma_f32_16x16x32_bf16 v[74:77], v[118:121], v[190:193], v[74:77]
	v_mfma_f32_16x16x32_bf16 v[74:77], v[106:109], v[178:181], v[74:77]
	s_setprio 0
	s_barrier
	ds_read_b128 v[150:153], v234 offset:16384
	ds_read_b128 v[154:157], v234 offset:17408
	ds_read_b128 v[158:161], v234 offset:18432
	ds_read_b128 v[162:165], v234 offset:19456
	ds_read_b128 v[170:173], v234 offset:20480
	ds_read_b128 v[174:177], v234 offset:21504
	ds_read_b128 v[178:181], v234 offset:22528
	ds_read_b128 v[190:193], v234 offset:23552
	s_add_i32 s58, s58, s24
	v_lshl_add_u64 v[214:215], s[56:57], 0, v[194:195]
	s_mov_b32 m0, s58
	s_nop 0
	global_load_lds_dwordx4 v194, s[56:57]
	s_add_i32 m0, s58, 0x2000
	v_lshl_add_u64 v[216:217], s[56:57], 0, v[204:205]
	s_add_u32 s56, s56, s12
	s_addc_u32 s57, s57, 0
	s_add_i32 s58, s59, s24
	global_load_lds_dwordx4 v[216:217], off
	v_lshl_add_u64 v[218:219], s[56:57], 0, v[194:195]
	s_mov_b32 m0, s58
	v_lshl_add_u64 v[220:221], s[56:57], 0, v[204:205]
	global_load_lds_dwordx4 v194, s[56:57]
	s_add_i32 m0, s58, 0x2000
	s_nop 0
	global_load_lds_dwordx4 v204, s[56:57]
	s_waitcnt vmcnt(6)
	s_waitcnt lgkmcnt(0)
	v_mfma_f32_16x16x32_bf16 v[62:65], v[66:69], v[150:153], v[62:65]
	v_mfma_f32_16x16x32_bf16 v[62:65], v[78:81], v[154:157], v[62:65]
	v_mfma_f32_16x16x32_bf16 v[58:61], v[98:101], v[154:157], v[58:61]
	v_mfma_f32_16x16x32_bf16 v[58:61], v[82:85], v[150:153], v[58:61]
	s_barrier
	s_setprio 1
	v_mfma_f32_16x16x32_bf16 v[42:45], v[82:85], v[158:161], v[42:45]
	v_mfma_f32_16x16x32_bf16 v[42:45], v[98:101], v[162:165], v[42:45]
	v_mfma_f32_16x16x32_bf16 v[46:49], v[78:81], v[162:165], v[46:49]
	v_mfma_f32_16x16x32_bf16 v[46:49], v[66:69], v[158:161], v[46:49]
	v_mfma_f32_16x16x32_bf16 v[30:33], v[66:69], v[170:173], v[30:33]
	v_mfma_f32_16x16x32_bf16 v[30:33], v[78:81], v[174:177], v[30:33]
	v_mfma_f32_16x16x32_bf16 v[26:29], v[98:101], v[174:177], v[26:29]
	v_mfma_f32_16x16x32_bf16 v[26:29], v[82:85], v[170:173], v[26:29]
	v_mfma_f32_16x16x32_bf16 v[10:13], v[82:85], v[178:181], v[10:13]
	v_mfma_f32_16x16x32_bf16 v[10:13], v[98:101], v[190:193], v[10:13]
	v_mfma_f32_16x16x32_bf16 v[14:17], v[78:81], v[190:193], v[14:17]
	v_mfma_f32_16x16x32_bf16 v[14:17], v[66:69], v[178:181], v[14:17]
	v_mfma_f32_16x16x32_bf16 v[54:57], v[106:109], v[150:153], v[54:57]
	v_mfma_f32_16x16x32_bf16 v[54:57], v[118:121], v[154:157], v[54:57]
	v_mfma_f32_16x16x32_bf16 v[50:53], v[142:145], v[154:157], v[50:53]
	v_mfma_f32_16x16x32_bf16 v[50:53], v[130:133], v[150:153], v[50:53]
	v_mfma_f32_16x16x32_bf16 v[34:37], v[130:133], v[158:161], v[34:37]
	v_mfma_f32_16x16x32_bf16 v[34:37], v[142:145], v[162:165], v[34:37]
	v_mfma_f32_16x16x32_bf16 v[38:41], v[118:121], v[162:165], v[38:41]
	v_mfma_f32_16x16x32_bf16 v[38:41], v[106:109], v[158:161], v[38:41]
	v_mfma_f32_16x16x32_bf16 v[22:25], v[106:109], v[170:173], v[22:25]
	v_mfma_f32_16x16x32_bf16 v[22:25], v[118:121], v[174:177], v[22:25]
	v_mfma_f32_16x16x32_bf16 v[18:21], v[142:145], v[174:177], v[18:21]
	v_mfma_f32_16x16x32_bf16 v[18:21], v[130:133], v[170:173], v[18:21]
	v_mfma_f32_16x16x32_bf16 v[2:5], v[130:133], v[178:181], v[2:5]
	v_mfma_f32_16x16x32_bf16 v[2:5], v[142:145], v[190:193], v[2:5]
	v_mfma_f32_16x16x32_bf16 v[6:9], v[118:121], v[190:193], v[6:9]
	v_mfma_f32_16x16x32_bf16 v[6:9], v[106:109], v[178:181], v[6:9]
	s_setprio 0
	s_barrier
	s_mov_b32 m0, s26
	s_nop 0
	global_load_lds_dwordx4 v208, s[20:21]
	s_mov_b32 m0, s27
	s_nop 0
	global_load_lds_dwordx4 v206, s[20:21]
	ds_read_b128 v[66:69], v198 offset:32768
	ds_read_b128 v[78:81], v198 offset:33792
	ds_read_b128 v[82:85], v198 offset:34816
	ds_read_b128 v[98:101], v198 offset:35840
	ds_read_b128 v[106:109], v198 offset:49152
	ds_read_b128 v[118:121], v198 offset:50176
	ds_read_b128 v[130:133], v198 offset:51200
	ds_read_b128 v[142:145], v198 offset:52224
	ds_read_b128 v[150:153], v234 offset:32768
	ds_read_b128 v[154:157], v234 offset:33792
	ds_read_b128 v[158:161], v234 offset:34816
	ds_read_b128 v[162:165], v234 offset:35840
	ds_read_b128 v[170:173], v234 offset:36864
	ds_read_b128 v[174:177], v234 offset:37888
	ds_read_b128 v[178:181], v234 offset:38912
	ds_read_b128 v[190:193], v234 offset:39936
	s_add_i32 s56, 0, 0x18000
	s_add_i32 s57, 0, 0x1c000
	s_add_u32 s20, s20, s12
	s_addc_u32 s21, s21, 0
	s_mov_b32 m0, s28
	s_nop 0
	global_load_lds_dwordx4 v208, s[20:21]
	s_mov_b32 m0, s29
	s_nop 0
	global_load_lds_dwordx4 v206, s[20:21]
	s_waitcnt vmcnt(8)
	s_waitcnt lgkmcnt(0)
	v_mfma_f32_16x16x32_bf16 v[186:189], v[66:69], v[150:153], v[186:189]
	v_mfma_f32_16x16x32_bf16 v[186:189], v[78:81], v[154:157], v[186:189]
	v_mfma_f32_16x16x32_bf16 v[182:185], v[98:101], v[154:157], v[182:185]
	v_mfma_f32_16x16x32_bf16 v[182:185], v[82:85], v[150:153], v[182:185]
	s_barrier
	s_setprio 1
	v_mfma_f32_16x16x32_bf16 v[134:137], v[82:85], v[158:161], v[134:137]
	v_mfma_f32_16x16x32_bf16 v[134:137], v[98:101], v[162:165], v[134:137]
	v_mfma_f32_16x16x32_bf16 v[138:141], v[78:81], v[162:165], v[138:141]
	v_mfma_f32_16x16x32_bf16 v[138:141], v[66:69], v[158:161], v[138:141]
	v_mfma_f32_16x16x32_bf16 v[114:117], v[66:69], v[170:173], v[114:117]
	v_mfma_f32_16x16x32_bf16 v[114:117], v[78:81], v[174:177], v[114:117]
	v_mfma_f32_16x16x32_bf16 v[110:113], v[98:101], v[174:177], v[110:113]
	v_mfma_f32_16x16x32_bf16 v[110:113], v[82:85], v[170:173], v[110:113]
	v_mfma_f32_16x16x32_bf16 v[86:89], v[82:85], v[178:181], v[86:89]
	v_mfma_f32_16x16x32_bf16 v[86:89], v[98:101], v[190:193], v[86:89]
	v_mfma_f32_16x16x32_bf16 v[90:93], v[78:81], v[190:193], v[90:93]
	v_mfma_f32_16x16x32_bf16 v[90:93], v[66:69], v[178:181], v[90:93]
	v_mfma_f32_16x16x32_bf16 v[166:169], v[106:109], v[150:153], v[166:169]
	v_mfma_f32_16x16x32_bf16 v[166:169], v[118:121], v[154:157], v[166:169]
	v_mfma_f32_16x16x32_bf16 v[146:149], v[142:145], v[154:157], v[146:149]
	v_mfma_f32_16x16x32_bf16 v[146:149], v[130:133], v[150:153], v[146:149]
	v_mfma_f32_16x16x32_bf16 v[122:125], v[130:133], v[158:161], v[122:125]
	v_mfma_f32_16x16x32_bf16 v[122:125], v[142:145], v[162:165], v[122:125]
	v_mfma_f32_16x16x32_bf16 v[126:129], v[118:121], v[162:165], v[126:129]
	v_mfma_f32_16x16x32_bf16 v[126:129], v[106:109], v[158:161], v[126:129]
	v_mfma_f32_16x16x32_bf16 v[102:105], v[106:109], v[170:173], v[102:105]
	v_mfma_f32_16x16x32_bf16 v[102:105], v[118:121], v[174:177], v[102:105]
	v_mfma_f32_16x16x32_bf16 v[94:97], v[142:145], v[174:177], v[94:97]
	v_mfma_f32_16x16x32_bf16 v[94:97], v[130:133], v[170:173], v[94:97]
	v_mfma_f32_16x16x32_bf16 v[70:73], v[130:133], v[178:181], v[70:73]
	v_mfma_f32_16x16x32_bf16 v[70:73], v[142:145], v[190:193], v[70:73]
	v_mfma_f32_16x16x32_bf16 v[74:77], v[118:121], v[190:193], v[74:77]
	v_mfma_f32_16x16x32_bf16 v[74:77], v[106:109], v[178:181], v[74:77]
	s_setprio 0
	s_barrier
	ds_read_b128 v[150:153], v234 offset:49152
	ds_read_b128 v[154:157], v234 offset:50176
	ds_read_b128 v[158:161], v234 offset:51200
	ds_read_b128 v[162:165], v234 offset:52224
	ds_read_b128 v[170:173], v234 offset:53248
	ds_read_b128 v[174:177], v234 offset:54272
	ds_read_b128 v[178:181], v234 offset:55296
	ds_read_b128 v[190:193], v234 offset:56320
	s_add_i32 s20, s56, s24
	v_lshl_add_u64 v[214:215], v[214:215], 0, s[94:95]
	s_mov_b32 m0, s20
	s_nop 0
	global_load_lds_dwordx4 v[214:215], off
	v_lshl_add_u64 v[214:215], v[216:217], 0, s[94:95]
	s_add_i32 m0, s20, 0x2000
	s_add_i32 s20, s57, s24
	global_load_lds_dwordx4 v[214:215], off
	v_lshl_add_u64 v[214:215], v[218:219], 0, s[94:95]
	s_mov_b32 m0, s20
	s_nop 0
	global_load_lds_dwordx4 v[214:215], off
	v_lshl_add_u64 v[214:215], v[220:221], 0, s[94:95]
	s_add_i32 m0, s20, 0x2000
	s_nop 0
	global_load_lds_dwordx4 v[214:215], off
	s_waitcnt vmcnt(6)
	s_waitcnt lgkmcnt(0)
	v_mfma_f32_16x16x32_bf16 v[62:65], v[66:69], v[150:153], v[62:65]
	v_mfma_f32_16x16x32_bf16 v[62:65], v[78:81], v[154:157], v[62:65]
	v_mfma_f32_16x16x32_bf16 v[58:61], v[98:101], v[154:157], v[58:61]
	v_mfma_f32_16x16x32_bf16 v[58:61], v[82:85], v[150:153], v[58:61]
	s_barrier
	s_setprio 1
	v_mfma_f32_16x16x32_bf16 v[42:45], v[82:85], v[158:161], v[42:45]
	v_mfma_f32_16x16x32_bf16 v[42:45], v[98:101], v[162:165], v[42:45]
	v_mfma_f32_16x16x32_bf16 v[46:49], v[78:81], v[162:165], v[46:49]
	v_mfma_f32_16x16x32_bf16 v[46:49], v[66:69], v[158:161], v[46:49]
	v_mfma_f32_16x16x32_bf16 v[30:33], v[66:69], v[170:173], v[30:33]
	v_mfma_f32_16x16x32_bf16 v[30:33], v[78:81], v[174:177], v[30:33]
	v_mfma_f32_16x16x32_bf16 v[26:29], v[98:101], v[174:177], v[26:29]
	v_mfma_f32_16x16x32_bf16 v[26:29], v[82:85], v[170:173], v[26:29]
	v_mfma_f32_16x16x32_bf16 v[10:13], v[82:85], v[178:181], v[10:13]
	v_mfma_f32_16x16x32_bf16 v[10:13], v[98:101], v[190:193], v[10:13]
	s_add_u32 s18, s18, 0x100
	v_mfma_f32_16x16x32_bf16 v[14:17], v[78:81], v[190:193], v[14:17]
	v_mfma_f32_16x16x32_bf16 v[14:17], v[66:69], v[178:181], v[14:17]
	s_addc_u32 s19, s19, 0
	v_mfma_f32_16x16x32_bf16 v[54:57], v[106:109], v[150:153], v[54:57]
	v_mfma_f32_16x16x32_bf16 v[54:57], v[118:121], v[154:157], v[54:57]
	s_add_u32 s51, s51, 0x100
	v_mfma_f32_16x16x32_bf16 v[50:53], v[142:145], v[154:157], v[50:53]
	v_mfma_f32_16x16x32_bf16 v[50:53], v[130:133], v[150:153], v[50:53]
	s_addc_u32 s54, s54, 0
	v_mfma_f32_16x16x32_bf16 v[34:37], v[130:133], v[158:161], v[34:37]
	v_mfma_f32_16x16x32_bf16 v[34:37], v[142:145], v[162:165], v[34:37]
	s_cmp_ge_u32 s55, s53
	v_mfma_f32_16x16x32_bf16 v[38:41], v[118:121], v[162:165], v[38:41]
	v_mfma_f32_16x16x32_bf16 v[38:41], v[106:109], v[158:161], v[38:41]
	s_mov_b32 s20, s55
	v_mfma_f32_16x16x32_bf16 v[22:25], v[106:109], v[170:173], v[22:25]
	v_mfma_f32_16x16x32_bf16 v[22:25], v[118:121], v[174:177], v[22:25]
	v_mfma_f32_16x16x32_bf16 v[18:21], v[142:145], v[174:177], v[18:21]
	v_mfma_f32_16x16x32_bf16 v[18:21], v[130:133], v[170:173], v[18:21]
	v_mfma_f32_16x16x32_bf16 v[2:5], v[130:133], v[178:181], v[2:5]
	v_mfma_f32_16x16x32_bf16 v[2:5], v[142:145], v[190:193], v[2:5]
	v_mfma_f32_16x16x32_bf16 v[6:9], v[118:121], v[190:193], v[6:9]
	v_mfma_f32_16x16x32_bf16 v[6:9], v[106:109], v[178:181], v[6:9]
	s_setprio 0
	s_barrier
	s_cbranch_scc0 .LBB0_850

.LBB0_875:
	s_sub_u32 vcc_lo, s20, s12
	s_subb_u32 vcc_hi, s21, 0
	s_mov_b32 m0, s51
	s_nop 0
	global_load_lds_dwordx4 v210, vcc
	s_mov_b32 m0, s53
	s_nop 0
	global_load_lds_dwordx4 v212, vcc
	ds_read_b128 v[130:133], v235
	ds_read_b128 v[134:137], v235 offset:1024
	ds_read_b128 v[138:141], v235 offset:2048
	ds_read_b128 v[142:145], v235 offset:3072
	ds_read_b128 v[146:149], v235 offset:16384
	ds_read_b128 v[150:153], v235 offset:17408
	ds_read_b128 v[154:157], v235 offset:18432
	ds_read_b128 v[158:161], v235 offset:19456
	ds_read_b128 v[162:165], v237
	ds_read_b128 v[166:169], v237 offset:1024
	ds_read_b128 v[170:173], v237 offset:2048
	ds_read_b128 v[174:177], v237 offset:3072
	ds_read_b128 v[178:181], v237 offset:4096
	ds_read_b128 v[182:185], v237 offset:5120
	ds_read_b128 v[186:189], v237 offset:6144
	ds_read_b128 v[190:193], v237 offset:7168
	s_add_i32 s29, s26, 2
	s_add_u32 s62, s20, 0x80
	s_addc_u32 s27, s21, 0
	s_add_i32 s64, 0, 0x10000
	s_cmp_eq_u32 s17, s26
	s_cselect_b32 s27, s7, s27
	s_cselect_b32 s26, s6, s62
	s_cselect_b32 s63, s19, s28
	s_cselect_b32 s62, s18, s23
	s_add_i32 s65, 0, 0x14000
	s_add_i32 m0, s37, 0xc000
	s_nop 0
	global_load_lds_dwordx4 v210, s[20:21]
	s_add_i32 m0, s37, 0xe000
	s_nop 0
	global_load_lds_dwordx4 v212, s[20:21]
	s_waitcnt vmcnt(8)
	s_waitcnt lgkmcnt(0)
	v_mfma_f32_16x16x32_bf16 v[126:129], v[130:133], v[162:165], v[126:129]
	v_mfma_f32_16x16x32_bf16 v[126:129], v[134:137], v[166:169], v[126:129]
	v_mfma_f32_16x16x32_bf16 v[122:125], v[142:145], v[166:169], v[122:125]
	v_mfma_f32_16x16x32_bf16 v[122:125], v[138:141], v[162:165], v[122:125]
	s_barrier
	s_setprio 1
	v_mfma_f32_16x16x32_bf16 v[106:109], v[138:141], v[170:173], v[106:109]
	v_mfma_f32_16x16x32_bf16 v[106:109], v[142:145], v[174:177], v[106:109]
	v_mfma_f32_16x16x32_bf16 v[110:113], v[134:137], v[174:177], v[110:113]
	v_mfma_f32_16x16x32_bf16 v[110:113], v[130:133], v[170:173], v[110:113]
	v_mfma_f32_16x16x32_bf16 v[94:97], v[130:133], v[178:181], v[94:97]
	v_mfma_f32_16x16x32_bf16 v[94:97], v[134:137], v[182:185], v[94:97]
	v_mfma_f32_16x16x32_bf16 v[90:93], v[142:145], v[182:185], v[90:93]
	v_mfma_f32_16x16x32_bf16 v[90:93], v[138:141], v[178:181], v[90:93]
	v_mfma_f32_16x16x32_bf16 v[74:77], v[138:141], v[186:189], v[74:77]
	v_mfma_f32_16x16x32_bf16 v[74:77], v[142:145], v[190:193], v[74:77]
	v_mfma_f32_16x16x32_bf16 v[78:81], v[134:137], v[190:193], v[78:81]
	v_mfma_f32_16x16x32_bf16 v[78:81], v[130:133], v[186:189], v[78:81]
	v_mfma_f32_16x16x32_bf16 v[118:121], v[146:149], v[162:165], v[118:121]
	v_mfma_f32_16x16x32_bf16 v[118:121], v[150:153], v[166:169], v[118:121]
	v_mfma_f32_16x16x32_bf16 v[114:117], v[158:161], v[166:169], v[114:117]
	v_mfma_f32_16x16x32_bf16 v[114:117], v[154:157], v[162:165], v[114:117]
	v_mfma_f32_16x16x32_bf16 v[98:101], v[154:157], v[170:173], v[98:101]
	v_mfma_f32_16x16x32_bf16 v[98:101], v[158:161], v[174:177], v[98:101]
	v_mfma_f32_16x16x32_bf16 v[102:105], v[150:153], v[174:177], v[102:105]
	v_mfma_f32_16x16x32_bf16 v[102:105], v[146:149], v[170:173], v[102:105]
	v_mfma_f32_16x16x32_bf16 v[86:89], v[146:149], v[178:181], v[86:89]
	v_mfma_f32_16x16x32_bf16 v[86:89], v[150:153], v[182:185], v[86:89]
	v_mfma_f32_16x16x32_bf16 v[82:85], v[158:161], v[182:185], v[82:85]
	v_mfma_f32_16x16x32_bf16 v[82:85], v[154:157], v[178:181], v[82:85]
	v_mfma_f32_16x16x32_bf16 v[66:69], v[154:157], v[186:189], v[66:69]
	v_mfma_f32_16x16x32_bf16 v[66:69], v[158:161], v[190:193], v[66:69]
	v_mfma_f32_16x16x32_bf16 v[70:73], v[150:153], v[190:193], v[70:73]
	v_mfma_f32_16x16x32_bf16 v[70:73], v[146:149], v[186:189], v[70:73]
	s_setprio 0
	s_barrier
	ds_read_b128 v[162:165], v237 offset:16384
	ds_read_b128 v[166:169], v237 offset:17408
	ds_read_b128 v[170:173], v237 offset:18432
	ds_read_b128 v[174:177], v237 offset:19456
	ds_read_b128 v[178:181], v237 offset:20480
	ds_read_b128 v[182:185], v237 offset:21504
	ds_read_b128 v[186:189], v237 offset:22528
	ds_read_b128 v[190:193], v237 offset:23552
	s_add_i32 s64, s64, s36
	v_lshl_add_u64 v[198:199], s[62:63], 0, v[194:195]
	s_mov_b32 m0, s64
	s_nop 0
	global_load_lds_dwordx4 v194, s[62:63]
	s_add_i32 m0, s64, 0x2000
	v_lshl_add_u64 v[214:215], s[62:63], 0, v[208:209]
	s_add_u32 s62, s62, s12
	s_addc_u32 s63, s63, 0
	s_add_i32 s64, s65, s36
	global_load_lds_dwordx4 v[214:215], off
	v_lshl_add_u64 v[216:217], s[62:63], 0, v[194:195]
	s_mov_b32 m0, s64
	v_lshl_add_u64 v[218:219], s[62:63], 0, v[208:209]
	global_load_lds_dwordx4 v194, s[62:63]
	s_add_i32 m0, s64, 0x2000
	s_nop 0
	global_load_lds_dwordx4 v208, s[62:63]
	s_waitcnt vmcnt(6)
	s_waitcnt lgkmcnt(0)
	v_mfma_f32_16x16x32_bf16 v[62:65], v[130:133], v[162:165], v[62:65]
	v_mfma_f32_16x16x32_bf16 v[62:65], v[134:137], v[166:169], v[62:65]
	v_mfma_f32_16x16x32_bf16 v[58:61], v[142:145], v[166:169], v[58:61]
	v_mfma_f32_16x16x32_bf16 v[58:61], v[138:141], v[162:165], v[58:61]
	s_barrier
	s_setprio 1
	v_mfma_f32_16x16x32_bf16 v[42:45], v[138:141], v[170:173], v[42:45]
	v_mfma_f32_16x16x32_bf16 v[42:45], v[142:145], v[174:177], v[42:45]
	v_mfma_f32_16x16x32_bf16 v[46:49], v[134:137], v[174:177], v[46:49]
	v_mfma_f32_16x16x32_bf16 v[46:49], v[130:133], v[170:173], v[46:49]
	v_mfma_f32_16x16x32_bf16 v[30:33], v[130:133], v[178:181], v[30:33]
	v_mfma_f32_16x16x32_bf16 v[30:33], v[134:137], v[182:185], v[30:33]
	v_mfma_f32_16x16x32_bf16 v[26:29], v[142:145], v[182:185], v[26:29]
	v_mfma_f32_16x16x32_bf16 v[26:29], v[138:141], v[178:181], v[26:29]
	v_mfma_f32_16x16x32_bf16 v[10:13], v[138:141], v[186:189], v[10:13]
	v_mfma_f32_16x16x32_bf16 v[10:13], v[142:145], v[190:193], v[10:13]
	v_mfma_f32_16x16x32_bf16 v[14:17], v[134:137], v[190:193], v[14:17]
	v_mfma_f32_16x16x32_bf16 v[14:17], v[130:133], v[186:189], v[14:17]
	v_mfma_f32_16x16x32_bf16 v[54:57], v[146:149], v[162:165], v[54:57]
	v_mfma_f32_16x16x32_bf16 v[54:57], v[150:153], v[166:169], v[54:57]
	v_mfma_f32_16x16x32_bf16 v[50:53], v[158:161], v[166:169], v[50:53]
	v_mfma_f32_16x16x32_bf16 v[50:53], v[154:157], v[162:165], v[50:53]
	v_mfma_f32_16x16x32_bf16 v[34:37], v[154:157], v[170:173], v[34:37]
	v_mfma_f32_16x16x32_bf16 v[34:37], v[158:161], v[174:177], v[34:37]
	v_mfma_f32_16x16x32_bf16 v[38:41], v[150:153], v[174:177], v[38:41]
	v_mfma_f32_16x16x32_bf16 v[38:41], v[146:149], v[170:173], v[38:41]
	v_mfma_f32_16x16x32_bf16 v[22:25], v[146:149], v[178:181], v[22:25]
	v_mfma_f32_16x16x32_bf16 v[22:25], v[150:153], v[182:185], v[22:25]
	v_mfma_f32_16x16x32_bf16 v[18:21], v[158:161], v[182:185], v[18:21]
	v_mfma_f32_16x16x32_bf16 v[18:21], v[154:157], v[178:181], v[18:21]
	v_mfma_f32_16x16x32_bf16 v[2:5], v[154:157], v[186:189], v[2:5]
	v_mfma_f32_16x16x32_bf16 v[2:5], v[158:161], v[190:193], v[2:5]
	v_mfma_f32_16x16x32_bf16 v[6:9], v[150:153], v[190:193], v[6:9]
	v_mfma_f32_16x16x32_bf16 v[6:9], v[146:149], v[186:189], v[6:9]
	s_setprio 0
	s_barrier
	s_mov_b32 m0, s37
	s_nop 0
	global_load_lds_dwordx4 v204, s[26:27]
	s_mov_b32 m0, s38
	s_nop 0
	global_load_lds_dwordx4 v206, s[26:27]
	ds_read_b128 v[130:133], v235 offset:32768
	ds_read_b128 v[134:137], v235 offset:33792
	ds_read_b128 v[138:141], v235 offset:34816
	ds_read_b128 v[142:145], v235 offset:35840
	ds_read_b128 v[146:149], v235 offset:49152
	ds_read_b128 v[150:153], v235 offset:50176
	ds_read_b128 v[154:157], v235 offset:51200
	ds_read_b128 v[158:161], v235 offset:52224
	ds_read_b128 v[162:165], v237 offset:32768
	ds_read_b128 v[166:169], v237 offset:33792
	ds_read_b128 v[170:173], v237 offset:34816
	ds_read_b128 v[174:177], v237 offset:35840
	ds_read_b128 v[178:181], v237 offset:36864
	ds_read_b128 v[182:185], v237 offset:37888
	ds_read_b128 v[186:189], v237 offset:38912
	ds_read_b128 v[190:193], v237 offset:39936
	s_add_i32 s62, 0, 0x18000
	s_add_i32 s63, 0, 0x1c000
	s_add_u32 s26, s26, s12
	s_addc_u32 s27, s27, 0
	s_mov_b32 m0, s39
	s_nop 0
	global_load_lds_dwordx4 v204, s[26:27]
	s_mov_b32 m0, s50
	s_nop 0
	global_load_lds_dwordx4 v206, s[26:27]
	s_waitcnt vmcnt(8)
	s_waitcnt lgkmcnt(0)
	v_mfma_f32_16x16x32_bf16 v[126:129], v[130:133], v[162:165], v[126:129]
	v_mfma_f32_16x16x32_bf16 v[126:129], v[134:137], v[166:169], v[126:129]
	v_mfma_f32_16x16x32_bf16 v[122:125], v[142:145], v[166:169], v[122:125]
	v_mfma_f32_16x16x32_bf16 v[122:125], v[138:141], v[162:165], v[122:125]
	s_barrier
	s_setprio 1
	v_mfma_f32_16x16x32_bf16 v[106:109], v[138:141], v[170:173], v[106:109]
	v_mfma_f32_16x16x32_bf16 v[106:109], v[142:145], v[174:177], v[106:109]
	v_mfma_f32_16x16x32_bf16 v[110:113], v[134:137], v[174:177], v[110:113]
	v_mfma_f32_16x16x32_bf16 v[110:113], v[130:133], v[170:173], v[110:113]
	v_mfma_f32_16x16x32_bf16 v[94:97], v[130:133], v[178:181], v[94:97]
	v_mfma_f32_16x16x32_bf16 v[94:97], v[134:137], v[182:185], v[94:97]
	v_mfma_f32_16x16x32_bf16 v[90:93], v[142:145], v[182:185], v[90:93]
	v_mfma_f32_16x16x32_bf16 v[90:93], v[138:141], v[178:181], v[90:93]
	v_mfma_f32_16x16x32_bf16 v[74:77], v[138:141], v[186:189], v[74:77]
	v_mfma_f32_16x16x32_bf16 v[74:77], v[142:145], v[190:193], v[74:77]
	v_mfma_f32_16x16x32_bf16 v[78:81], v[134:137], v[190:193], v[78:81]
	v_mfma_f32_16x16x32_bf16 v[78:81], v[130:133], v[186:189], v[78:81]
	v_mfma_f32_16x16x32_bf16 v[118:121], v[146:149], v[162:165], v[118:121]
	v_mfma_f32_16x16x32_bf16 v[118:121], v[150:153], v[166:169], v[118:121]
	v_mfma_f32_16x16x32_bf16 v[114:117], v[158:161], v[166:169], v[114:117]
	v_mfma_f32_16x16x32_bf16 v[114:117], v[154:157], v[162:165], v[114:117]
	v_mfma_f32_16x16x32_bf16 v[98:101], v[154:157], v[170:173], v[98:101]
	v_mfma_f32_16x16x32_bf16 v[98:101], v[158:161], v[174:177], v[98:101]
	v_mfma_f32_16x16x32_bf16 v[102:105], v[150:153], v[174:177], v[102:105]
	v_mfma_f32_16x16x32_bf16 v[102:105], v[146:149], v[170:173], v[102:105]
	v_mfma_f32_16x16x32_bf16 v[86:89], v[146:149], v[178:181], v[86:89]
	v_mfma_f32_16x16x32_bf16 v[86:89], v[150:153], v[182:185], v[86:89]
	v_mfma_f32_16x16x32_bf16 v[82:85], v[158:161], v[182:185], v[82:85]
	v_mfma_f32_16x16x32_bf16 v[82:85], v[154:157], v[178:181], v[82:85]
	v_mfma_f32_16x16x32_bf16 v[66:69], v[154:157], v[186:189], v[66:69]
	v_mfma_f32_16x16x32_bf16 v[66:69], v[158:161], v[190:193], v[66:69]
	v_mfma_f32_16x16x32_bf16 v[70:73], v[150:153], v[190:193], v[70:73]
	v_mfma_f32_16x16x32_bf16 v[70:73], v[146:149], v[186:189], v[70:73]
	s_setprio 0
	s_barrier
	ds_read_b128 v[162:165], v237 offset:49152
	ds_read_b128 v[166:169], v237 offset:50176
	ds_read_b128 v[170:173], v237 offset:51200
	ds_read_b128 v[174:177], v237 offset:52224
	ds_read_b128 v[178:181], v237 offset:53248
	ds_read_b128 v[182:185], v237 offset:54272
	ds_read_b128 v[186:189], v237 offset:55296
	ds_read_b128 v[190:193], v237 offset:56320
	s_add_i32 s26, s62, s36
	v_lshl_add_u64 v[198:199], v[198:199], 0, s[94:95]
	s_mov_b32 m0, s26
	s_nop 0
	global_load_lds_dwordx4 v[198:199], off
	v_lshl_add_u64 v[198:199], v[214:215], 0, s[94:95]
	s_add_i32 m0, s26, 0x2000
	s_add_i32 s26, s63, s36
	global_load_lds_dwordx4 v[198:199], off
	v_lshl_add_u64 v[198:199], v[216:217], 0, s[94:95]
	s_mov_b32 m0, s26
	s_nop 0
	global_load_lds_dwordx4 v[198:199], off
	v_lshl_add_u64 v[198:199], v[218:219], 0, s[94:95]
	s_add_i32 m0, s26, 0x2000
	s_nop 0
	global_load_lds_dwordx4 v[198:199], off
	s_waitcnt vmcnt(6)
	s_waitcnt lgkmcnt(0)
	v_mfma_f32_16x16x32_bf16 v[62:65], v[130:133], v[162:165], v[62:65]
	v_mfma_f32_16x16x32_bf16 v[62:65], v[134:137], v[166:169], v[62:65]
	v_mfma_f32_16x16x32_bf16 v[58:61], v[142:145], v[166:169], v[58:61]
	v_mfma_f32_16x16x32_bf16 v[58:61], v[138:141], v[162:165], v[58:61]
	s_barrier
	s_setprio 1
	v_mfma_f32_16x16x32_bf16 v[42:45], v[138:141], v[170:173], v[42:45]
	v_mfma_f32_16x16x32_bf16 v[42:45], v[142:145], v[174:177], v[42:45]
	v_mfma_f32_16x16x32_bf16 v[46:49], v[134:137], v[174:177], v[46:49]
	v_mfma_f32_16x16x32_bf16 v[46:49], v[130:133], v[170:173], v[46:49]
	v_mfma_f32_16x16x32_bf16 v[30:33], v[130:133], v[178:181], v[30:33]
	v_mfma_f32_16x16x32_bf16 v[30:33], v[134:137], v[182:185], v[30:33]
	v_mfma_f32_16x16x32_bf16 v[26:29], v[142:145], v[182:185], v[26:29]
	v_mfma_f32_16x16x32_bf16 v[26:29], v[138:141], v[178:181], v[26:29]
	v_mfma_f32_16x16x32_bf16 v[10:13], v[138:141], v[186:189], v[10:13]
	v_mfma_f32_16x16x32_bf16 v[10:13], v[142:145], v[190:193], v[10:13]
	s_add_u32 s20, s20, 0x100
	v_mfma_f32_16x16x32_bf16 v[14:17], v[134:137], v[190:193], v[14:17]
	v_mfma_f32_16x16x32_bf16 v[14:17], v[130:133], v[186:189], v[14:17]
	s_addc_u32 s21, s21, 0
	v_mfma_f32_16x16x32_bf16 v[54:57], v[146:149], v[162:165], v[54:57]
	v_mfma_f32_16x16x32_bf16 v[54:57], v[150:153], v[166:169], v[54:57]
	s_add_u32 s23, s23, 0x100
	v_mfma_f32_16x16x32_bf16 v[50:53], v[158:161], v[166:169], v[50:53]
	v_mfma_f32_16x16x32_bf16 v[50:53], v[154:157], v[162:165], v[50:53]
	s_addc_u32 s28, s28, 0
	v_mfma_f32_16x16x32_bf16 v[34:37], v[154:157], v[170:173], v[34:37]
	v_mfma_f32_16x16x32_bf16 v[34:37], v[158:161], v[174:177], v[34:37]
	s_cmp_ge_i32 s29, s25
	v_mfma_f32_16x16x32_bf16 v[38:41], v[150:153], v[174:177], v[38:41]
	v_mfma_f32_16x16x32_bf16 v[38:41], v[146:149], v[170:173], v[38:41]
	s_mov_b32 s26, s29
	v_mfma_f32_16x16x32_bf16 v[22:25], v[146:149], v[178:181], v[22:25]
	v_mfma_f32_16x16x32_bf16 v[22:25], v[150:153], v[182:185], v[22:25]
	v_mfma_f32_16x16x32_bf16 v[18:21], v[158:161], v[182:185], v[18:21]
	v_mfma_f32_16x16x32_bf16 v[18:21], v[154:157], v[178:181], v[18:21]
	v_mfma_f32_16x16x32_bf16 v[2:5], v[154:157], v[186:189], v[2:5]
	v_mfma_f32_16x16x32_bf16 v[2:5], v[158:161], v[190:193], v[2:5]
	v_mfma_f32_16x16x32_bf16 v[6:9], v[150:153], v[190:193], v[6:9]
	v_mfma_f32_16x16x32_bf16 v[6:9], v[146:149], v[186:189], v[6:9]
	s_setprio 0
	s_barrier
	s_cbranch_scc0 .LBB0_875
	v_readlane_b32 s64, v254, 51
	v_readlane_b32 s65, v254, 52
	s_branch .LBB0_878

.LBB0_973:
	s_add_u32 vcc_lo, s0, 0xffffc000
	s_addc_u32 vcc_hi, s1, -1
	s_mov_b32 m0, s59
	s_nop 0
	global_load_lds_dwordx4 v146, vcc
	s_mov_b32 m0, s60
	s_nop 0
	global_load_lds_dwordx4 v148, vcc
	ds_read_b128 v[130:133], v246
	ds_read_b128 v[134:137], v246 offset:1024
	ds_read_b128 v[150:153], v246 offset:2048
	ds_read_b128 v[154:157], v246 offset:3072
	ds_read_b128 v[158:161], v246 offset:16384
	ds_read_b128 v[162:165], v246 offset:17408
	ds_read_b128 v[166:169], v246 offset:18432
	ds_read_b128 v[170:173], v246 offset:19456
	ds_read_b128 v[174:177], v247
	ds_read_b128 v[178:181], v247 offset:1024
	ds_read_b128 v[182:185], v247 offset:2048
	ds_read_b128 v[186:189], v247 offset:3072
	ds_read_b128 v[190:193], v247 offset:4096
	ds_read_b128 v[204:207], v247 offset:5120
	ds_read_b128 v[208:211], v247 offset:6144
	ds_read_b128 v[212:215], v247 offset:7168
	s_add_u32 s4, s0, 0x100
	s_addc_u32 s5, s1, 0
	s_add_i32 s40, 0, 0x10000
	s_cmp_eq_u32 s39, 28
	s_cselect_b32 s11, s35, s5
	s_cselect_b32 s10, s34, s4
	s_cselect_b32 s7, s13, s38
	s_cselect_b32 s6, s29, s33
	s_add_i32 s41, 0, 0x14000
	s_add_i32 m0, s49, 0xc000
	s_nop 0
	global_load_lds_dwordx4 v146, s[0:1]
	s_add_i32 m0, s49, 0xe000
	s_nop 0
	global_load_lds_dwordx4 v148, s[0:1]
	s_waitcnt vmcnt(8)
	s_waitcnt lgkmcnt(0)
	v_mfma_f32_16x16x32_bf16 v[126:129], v[130:133], v[174:177], v[126:129]
	v_mfma_f32_16x16x32_bf16 v[126:129], v[134:137], v[178:181], v[126:129]
	v_mfma_f32_16x16x32_bf16 v[62:65], v[154:157], v[178:181], v[62:65]
	v_mfma_f32_16x16x32_bf16 v[62:65], v[150:153], v[174:177], v[62:65]
	s_barrier
	s_setprio 1
	v_mfma_f32_16x16x32_bf16 v[58:61], v[150:153], v[182:185], v[58:61]
	v_mfma_f32_16x16x32_bf16 v[58:61], v[154:157], v[186:189], v[58:61]
	v_mfma_f32_16x16x32_bf16 v[122:125], v[134:137], v[186:189], v[122:125]
	v_mfma_f32_16x16x32_bf16 v[122:125], v[130:133], v[182:185], v[122:125]
	v_mfma_f32_16x16x32_bf16 v[114:117], v[130:133], v[190:193], v[114:117]
	v_mfma_f32_16x16x32_bf16 v[114:117], v[134:137], v[204:207], v[114:117]
	v_mfma_f32_16x16x32_bf16 v[50:53], v[154:157], v[204:207], v[50:53]
	v_mfma_f32_16x16x32_bf16 v[50:53], v[150:153], v[190:193], v[50:53]
	v_mfma_f32_16x16x32_bf16 v[42:45], v[150:153], v[208:211], v[42:45]
	v_mfma_f32_16x16x32_bf16 v[42:45], v[154:157], v[212:215], v[42:45]
	v_mfma_f32_16x16x32_bf16 v[106:109], v[134:137], v[212:215], v[106:109]
	v_mfma_f32_16x16x32_bf16 v[106:109], v[130:133], v[208:211], v[106:109]
	v_mfma_f32_16x16x32_bf16 v[118:121], v[158:161], v[174:177], v[118:121]
	v_mfma_f32_16x16x32_bf16 v[118:121], v[162:165], v[178:181], v[118:121]
	v_mfma_f32_16x16x32_bf16 v[54:57], v[170:173], v[178:181], v[54:57]
	v_mfma_f32_16x16x32_bf16 v[54:57], v[166:169], v[174:177], v[54:57]
	v_mfma_f32_16x16x32_bf16 v[46:49], v[166:169], v[182:185], v[46:49]
	v_mfma_f32_16x16x32_bf16 v[46:49], v[170:173], v[186:189], v[46:49]
	v_mfma_f32_16x16x32_bf16 v[110:113], v[162:165], v[186:189], v[110:113]
	v_mfma_f32_16x16x32_bf16 v[110:113], v[158:161], v[182:185], v[110:113]
	v_mfma_f32_16x16x32_bf16 v[102:105], v[158:161], v[190:193], v[102:105]
	v_mfma_f32_16x16x32_bf16 v[102:105], v[162:165], v[204:207], v[102:105]
	v_mfma_f32_16x16x32_bf16 v[38:41], v[170:173], v[204:207], v[38:41]
	v_mfma_f32_16x16x32_bf16 v[38:41], v[166:169], v[190:193], v[38:41]
	v_mfma_f32_16x16x32_bf16 v[34:37], v[166:169], v[208:211], v[34:37]
	v_mfma_f32_16x16x32_bf16 v[34:37], v[170:173], v[212:215], v[34:37]
	v_mfma_f32_16x16x32_bf16 v[98:101], v[162:165], v[212:215], v[98:101]
	v_mfma_f32_16x16x32_bf16 v[98:101], v[158:161], v[208:211], v[98:101]
	s_setprio 0
	s_barrier
	ds_read_b128 v[174:177], v247 offset:16384
	ds_read_b128 v[178:181], v247 offset:17408
	ds_read_b128 v[182:185], v247 offset:18432
	ds_read_b128 v[186:189], v247 offset:19456
	ds_read_b128 v[190:193], v247 offset:20480
	ds_read_b128 v[204:207], v247 offset:21504
	ds_read_b128 v[208:211], v247 offset:22528
	ds_read_b128 v[212:215], v247 offset:23552
	s_add_i32 s0, s40, s48
	s_mov_b32 m0, s0
	s_nop 0
	global_load_lds_dwordx4 v140, s[6:7]
	s_add_i32 m0, s0, 0x2000
	s_add_u32 s0, s6, 0x80000
	s_addc_u32 s1, s7, 0
	s_add_i32 s40, s41, s48
	global_load_lds_dwordx4 v144, s[6:7]
	s_mov_b32 m0, s40
	s_nop 0
	global_load_lds_dwordx4 v140, s[0:1]
	s_add_i32 m0, s40, 0x2000
	s_nop 0
	global_load_lds_dwordx4 v144, s[0:1]
	s_waitcnt vmcnt(6)
	s_waitcnt lgkmcnt(0)
	v_mfma_f32_16x16x32_bf16 v[94:97], v[130:133], v[174:177], v[94:97]
	v_mfma_f32_16x16x32_bf16 v[94:97], v[134:137], v[178:181], v[94:97]
	v_mfma_f32_16x16x32_bf16 v[30:33], v[154:157], v[178:181], v[30:33]
	v_mfma_f32_16x16x32_bf16 v[30:33], v[150:153], v[174:177], v[30:33]
	s_barrier
	s_setprio 1
	v_mfma_f32_16x16x32_bf16 v[26:29], v[150:153], v[182:185], v[26:29]
	v_mfma_f32_16x16x32_bf16 v[26:29], v[154:157], v[186:189], v[26:29]
	v_mfma_f32_16x16x32_bf16 v[90:93], v[134:137], v[186:189], v[90:93]
	v_mfma_f32_16x16x32_bf16 v[90:93], v[130:133], v[182:185], v[90:93]
	v_mfma_f32_16x16x32_bf16 v[82:85], v[130:133], v[190:193], v[82:85]
	v_mfma_f32_16x16x32_bf16 v[82:85], v[134:137], v[204:207], v[82:85]
	v_mfma_f32_16x16x32_bf16 v[18:21], v[154:157], v[204:207], v[18:21]
	v_mfma_f32_16x16x32_bf16 v[18:21], v[150:153], v[190:193], v[18:21]
	v_mfma_f32_16x16x32_bf16 v[10:13], v[150:153], v[208:211], v[10:13]
	v_mfma_f32_16x16x32_bf16 v[10:13], v[154:157], v[212:215], v[10:13]
	v_mfma_f32_16x16x32_bf16 v[74:77], v[134:137], v[212:215], v[74:77]
	v_mfma_f32_16x16x32_bf16 v[74:77], v[130:133], v[208:211], v[74:77]
	v_mfma_f32_16x16x32_bf16 v[86:89], v[158:161], v[174:177], v[86:89]
	v_mfma_f32_16x16x32_bf16 v[86:89], v[162:165], v[178:181], v[86:89]
	v_mfma_f32_16x16x32_bf16 v[22:25], v[170:173], v[178:181], v[22:25]
	v_mfma_f32_16x16x32_bf16 v[22:25], v[166:169], v[174:177], v[22:25]
	v_mfma_f32_16x16x32_bf16 v[14:17], v[166:169], v[182:185], v[14:17]
	v_mfma_f32_16x16x32_bf16 v[14:17], v[170:173], v[186:189], v[14:17]
	v_mfma_f32_16x16x32_bf16 v[78:81], v[162:165], v[186:189], v[78:81]
	v_mfma_f32_16x16x32_bf16 v[78:81], v[158:161], v[182:185], v[78:81]
	v_mfma_f32_16x16x32_bf16 v[70:73], v[158:161], v[190:193], v[70:73]
	v_mfma_f32_16x16x32_bf16 v[70:73], v[162:165], v[204:207], v[70:73]
	v_mfma_f32_16x16x32_bf16 v[6:9], v[170:173], v[204:207], v[6:9]
	v_mfma_f32_16x16x32_bf16 v[6:9], v[166:169], v[190:193], v[6:9]
	v_mfma_f32_16x16x32_bf16 v[2:5], v[166:169], v[208:211], v[2:5]
	v_mfma_f32_16x16x32_bf16 v[2:5], v[170:173], v[212:215], v[2:5]
	v_mfma_f32_16x16x32_bf16 v[66:69], v[162:165], v[212:215], v[66:69]
	v_mfma_f32_16x16x32_bf16 v[66:69], v[158:161], v[208:211], v[66:69]
	s_setprio 0
	s_barrier
	s_mov_b32 m0, s49
	s_nop 0
	global_load_lds_dwordx4 v138, s[10:11]
	s_mov_b32 m0, s70
	s_nop 0
	global_load_lds_dwordx4 v142, s[10:11]
	ds_read_b128 v[130:133], v246 offset:32768
	ds_read_b128 v[134:137], v246 offset:33792
	ds_read_b128 v[150:153], v246 offset:34816
	ds_read_b128 v[154:157], v246 offset:35840
	ds_read_b128 v[158:161], v246 offset:49152
	ds_read_b128 v[162:165], v246 offset:50176
	ds_read_b128 v[166:169], v246 offset:51200
	ds_read_b128 v[170:173], v246 offset:52224
	ds_read_b128 v[174:177], v247 offset:32768
	ds_read_b128 v[178:181], v247 offset:33792
	ds_read_b128 v[182:185], v247 offset:34816
	ds_read_b128 v[186:189], v247 offset:35840
	ds_read_b128 v[190:193], v247 offset:36864
	ds_read_b128 v[204:207], v247 offset:37888
	ds_read_b128 v[208:211], v247 offset:38912
	ds_read_b128 v[212:215], v247 offset:39936
	s_add_i32 s40, 0, 0x18000
	s_add_i32 s41, 0, 0x1c000
	s_add_u32 s0, s10, 0x4000
	s_addc_u32 s1, s11, 0
	s_mov_b32 m0, s71
	s_nop 0
	global_load_lds_dwordx4 v138, s[0:1]
	s_mov_b32 m0, s73
	s_nop 0
	global_load_lds_dwordx4 v142, s[0:1]
	s_waitcnt vmcnt(8)
	s_waitcnt lgkmcnt(0)
	v_mfma_f32_16x16x32_bf16 v[126:129], v[130:133], v[174:177], v[126:129]
	v_mfma_f32_16x16x32_bf16 v[126:129], v[134:137], v[178:181], v[126:129]
	v_mfma_f32_16x16x32_bf16 v[62:65], v[154:157], v[178:181], v[62:65]
	v_mfma_f32_16x16x32_bf16 v[62:65], v[150:153], v[174:177], v[62:65]
	s_barrier
	s_setprio 1
	v_mfma_f32_16x16x32_bf16 v[58:61], v[150:153], v[182:185], v[58:61]
	v_mfma_f32_16x16x32_bf16 v[58:61], v[154:157], v[186:189], v[58:61]
	v_mfma_f32_16x16x32_bf16 v[122:125], v[134:137], v[186:189], v[122:125]
	v_mfma_f32_16x16x32_bf16 v[122:125], v[130:133], v[182:185], v[122:125]
	v_mfma_f32_16x16x32_bf16 v[114:117], v[130:133], v[190:193], v[114:117]
	v_mfma_f32_16x16x32_bf16 v[114:117], v[134:137], v[204:207], v[114:117]
	v_mfma_f32_16x16x32_bf16 v[50:53], v[154:157], v[204:207], v[50:53]
	v_mfma_f32_16x16x32_bf16 v[50:53], v[150:153], v[190:193], v[50:53]
	v_mfma_f32_16x16x32_bf16 v[42:45], v[150:153], v[208:211], v[42:45]
	v_mfma_f32_16x16x32_bf16 v[42:45], v[154:157], v[212:215], v[42:45]
	v_mfma_f32_16x16x32_bf16 v[106:109], v[134:137], v[212:215], v[106:109]
	v_mfma_f32_16x16x32_bf16 v[106:109], v[130:133], v[208:211], v[106:109]
	v_mfma_f32_16x16x32_bf16 v[118:121], v[158:161], v[174:177], v[118:121]
	v_mfma_f32_16x16x32_bf16 v[118:121], v[162:165], v[178:181], v[118:121]
	v_mfma_f32_16x16x32_bf16 v[54:57], v[170:173], v[178:181], v[54:57]
	v_mfma_f32_16x16x32_bf16 v[54:57], v[166:169], v[174:177], v[54:57]
	v_mfma_f32_16x16x32_bf16 v[46:49], v[166:169], v[182:185], v[46:49]
	v_mfma_f32_16x16x32_bf16 v[46:49], v[170:173], v[186:189], v[46:49]
	v_mfma_f32_16x16x32_bf16 v[110:113], v[162:165], v[186:189], v[110:113]
	v_mfma_f32_16x16x32_bf16 v[110:113], v[158:161], v[182:185], v[110:113]
	v_mfma_f32_16x16x32_bf16 v[102:105], v[158:161], v[190:193], v[102:105]
	v_mfma_f32_16x16x32_bf16 v[102:105], v[162:165], v[204:207], v[102:105]
	v_mfma_f32_16x16x32_bf16 v[38:41], v[170:173], v[204:207], v[38:41]
	v_mfma_f32_16x16x32_bf16 v[38:41], v[166:169], v[190:193], v[38:41]
	v_mfma_f32_16x16x32_bf16 v[34:37], v[166:169], v[208:211], v[34:37]
	v_mfma_f32_16x16x32_bf16 v[34:37], v[170:173], v[212:215], v[34:37]
	v_mfma_f32_16x16x32_bf16 v[98:101], v[162:165], v[212:215], v[98:101]
	v_mfma_f32_16x16x32_bf16 v[98:101], v[158:161], v[208:211], v[98:101]
	s_setprio 0
	s_barrier
	ds_read_b128 v[174:177], v247 offset:49152
	ds_read_b128 v[178:181], v247 offset:50176
	ds_read_b128 v[182:185], v247 offset:51200
	ds_read_b128 v[186:189], v247 offset:52224
	ds_read_b128 v[190:193], v247 offset:53248
	ds_read_b128 v[204:207], v247 offset:54272
	ds_read_b128 v[208:211], v247 offset:55296
	ds_read_b128 v[212:215], v247 offset:56320
	s_add_i32 s0, s40, s48
	s_add_u32 vcc_lo, s6, s94
	s_addc_u32 vcc_hi, s7, s95
	s_mov_b32 m0, s0
	s_nop 0
	global_load_lds_dwordx4 v140, vcc
	s_add_i32 m0, s0, 0x2000
	s_add_u32 s0, s6, 0x80080
	s_addc_u32 s1, s7, 0
	s_add_i32 s6, s41, s48
	global_load_lds_dwordx4 v144, vcc
	s_mov_b32 m0, s6
	s_nop 0
	global_load_lds_dwordx4 v140, s[0:1]
	s_add_i32 m0, s6, 0x2000
	s_nop 0
	global_load_lds_dwordx4 v144, s[0:1]
	s_waitcnt vmcnt(6)
	s_waitcnt lgkmcnt(0)
	v_mfma_f32_16x16x32_bf16 v[94:97], v[130:133], v[174:177], v[94:97]
	v_mfma_f32_16x16x32_bf16 v[94:97], v[134:137], v[178:181], v[94:97]
	v_mfma_f32_16x16x32_bf16 v[30:33], v[154:157], v[178:181], v[30:33]
	v_mfma_f32_16x16x32_bf16 v[30:33], v[150:153], v[174:177], v[30:33]
	s_barrier
	s_setprio 1
	v_mfma_f32_16x16x32_bf16 v[26:29], v[150:153], v[182:185], v[26:29]
	v_mfma_f32_16x16x32_bf16 v[26:29], v[154:157], v[186:189], v[26:29]
	v_mfma_f32_16x16x32_bf16 v[90:93], v[134:137], v[186:189], v[90:93]
	v_mfma_f32_16x16x32_bf16 v[90:93], v[130:133], v[182:185], v[90:93]
	v_mfma_f32_16x16x32_bf16 v[82:85], v[130:133], v[190:193], v[82:85]
	v_mfma_f32_16x16x32_bf16 v[82:85], v[134:137], v[204:207], v[82:85]
	v_mfma_f32_16x16x32_bf16 v[18:21], v[154:157], v[204:207], v[18:21]
	v_mfma_f32_16x16x32_bf16 v[18:21], v[150:153], v[190:193], v[18:21]
	v_mfma_f32_16x16x32_bf16 v[10:13], v[150:153], v[208:211], v[10:13]
	v_mfma_f32_16x16x32_bf16 v[10:13], v[154:157], v[212:215], v[10:13]
	s_add_i32 s39, s39, 2
	v_mfma_f32_16x16x32_bf16 v[74:77], v[134:137], v[212:215], v[74:77]
	v_mfma_f32_16x16x32_bf16 v[74:77], v[130:133], v[208:211], v[74:77]
	s_add_u32 s33, s33, 0x100
	v_mfma_f32_16x16x32_bf16 v[86:89], v[158:161], v[174:177], v[86:89]
	v_mfma_f32_16x16x32_bf16 v[86:89], v[162:165], v[178:181], v[86:89]
	s_addc_u32 s38, s38, 0
	v_mfma_f32_16x16x32_bf16 v[22:25], v[170:173], v[178:181], v[22:25]
	v_mfma_f32_16x16x32_bf16 v[22:25], v[166:169], v[174:177], v[22:25]
	s_cmp_gt_u32 s39, 29
	v_mfma_f32_16x16x32_bf16 v[14:17], v[166:169], v[182:185], v[14:17]
	v_mfma_f32_16x16x32_bf16 v[14:17], v[170:173], v[186:189], v[14:17]
	s_mov_b64 s[0:1], s[4:5]
	v_mfma_f32_16x16x32_bf16 v[78:81], v[162:165], v[186:189], v[78:81]
	v_mfma_f32_16x16x32_bf16 v[78:81], v[158:161], v[182:185], v[78:81]
	v_mfma_f32_16x16x32_bf16 v[70:73], v[158:161], v[190:193], v[70:73]
	v_mfma_f32_16x16x32_bf16 v[70:73], v[162:165], v[204:207], v[70:73]
	v_mfma_f32_16x16x32_bf16 v[6:9], v[170:173], v[204:207], v[6:9]
	v_mfma_f32_16x16x32_bf16 v[6:9], v[166:169], v[190:193], v[6:9]
	v_mfma_f32_16x16x32_bf16 v[2:5], v[166:169], v[208:211], v[2:5]
	v_mfma_f32_16x16x32_bf16 v[2:5], v[170:173], v[212:215], v[2:5]
	v_mfma_f32_16x16x32_bf16 v[66:69], v[162:165], v[212:215], v[66:69]
	v_mfma_f32_16x16x32_bf16 v[66:69], v[158:161], v[208:211], v[66:69]
	s_setprio 0
	s_barrier
	s_cbranch_scc0 .LBB0_973

.LBB0_1441:
	s_add_u32 vcc_lo, s18, 0xffea0000
	s_addc_u32 vcc_hi, s19, -1
	s_mov_b32 m0, s38
	s_nop 0
	global_load_lds_dwordx4 v210, vcc
	s_mov_b32 m0, s40
	s_nop 0
	global_load_lds_dwordx4 v212, vcc
	ds_read_b128 v[66:69], v198
	ds_read_b128 v[78:81], v198 offset:1024
	ds_read_b128 v[86:89], v198 offset:2048
	ds_read_b128 v[98:101], v198 offset:3072
	ds_read_b128 v[106:109], v198 offset:16384
	ds_read_b128 v[118:121], v198 offset:17408
	ds_read_b128 v[130:133], v198 offset:18432
	ds_read_b128 v[142:145], v198 offset:19456
	ds_read_b128 v[150:153], v234
	ds_read_b128 v[154:157], v234 offset:1024
	ds_read_b128 v[158:161], v234 offset:2048
	ds_read_b128 v[162:165], v234 offset:3072
	ds_read_b128 v[170:173], v234 offset:4096
	ds_read_b128 v[174:177], v234 offset:5120
	ds_read_b128 v[178:181], v234 offset:6144
	ds_read_b128 v[190:193], v234 offset:7168
	s_add_u32 s20, s18, 0x100
	s_addc_u32 s21, s19, 0
	s_add_i32 s49, 0, 0x10000
	s_cmpk_eq_i32 s48, 0x54
	s_cselect_b32 s25, s1, s21
	s_cselect_b32 s24, s0, s20
	s_cselect_b32 s23, s17, s47
	s_cselect_b32 s22, s16, s46
	s_add_i32 s50, 0, 0x14000
	s_add_i32 m0, s28, 0xc000
	s_nop 0
	global_load_lds_dwordx4 v210, s[18:19]
	s_add_i32 m0, s28, 0xe000
	s_nop 0
	global_load_lds_dwordx4 v212, s[18:19]
	s_waitcnt vmcnt(8)
	s_waitcnt lgkmcnt(0)
	v_mfma_f32_16x16x32_bf16 v[186:189], v[66:69], v[150:153], v[186:189]
	v_mfma_f32_16x16x32_bf16 v[186:189], v[78:81], v[154:157], v[186:189]
	v_mfma_f32_16x16x32_bf16 v[182:185], v[98:101], v[154:157], v[182:185]
	v_mfma_f32_16x16x32_bf16 v[182:185], v[86:89], v[150:153], v[182:185]
	s_barrier
	s_setprio 1
	v_mfma_f32_16x16x32_bf16 v[134:137], v[86:89], v[158:161], v[134:137]
	v_mfma_f32_16x16x32_bf16 v[134:137], v[98:101], v[162:165], v[134:137]
	v_mfma_f32_16x16x32_bf16 v[138:141], v[78:81], v[162:165], v[138:141]
	v_mfma_f32_16x16x32_bf16 v[138:141], v[66:69], v[158:161], v[138:141]
	v_mfma_f32_16x16x32_bf16 v[114:117], v[66:69], v[170:173], v[114:117]
	v_mfma_f32_16x16x32_bf16 v[114:117], v[78:81], v[174:177], v[114:117]
	v_mfma_f32_16x16x32_bf16 v[110:113], v[98:101], v[174:177], v[110:113]
	v_mfma_f32_16x16x32_bf16 v[110:113], v[86:89], v[170:173], v[110:113]
	v_mfma_f32_16x16x32_bf16 v[82:85], v[86:89], v[178:181], v[82:85]
	v_mfma_f32_16x16x32_bf16 v[82:85], v[98:101], v[190:193], v[82:85]
	v_mfma_f32_16x16x32_bf16 v[90:93], v[78:81], v[190:193], v[90:93]
	v_mfma_f32_16x16x32_bf16 v[90:93], v[66:69], v[178:181], v[90:93]
	v_mfma_f32_16x16x32_bf16 v[166:169], v[106:109], v[150:153], v[166:169]
	v_mfma_f32_16x16x32_bf16 v[166:169], v[118:121], v[154:157], v[166:169]
	v_mfma_f32_16x16x32_bf16 v[146:149], v[142:145], v[154:157], v[146:149]
	v_mfma_f32_16x16x32_bf16 v[146:149], v[130:133], v[150:153], v[146:149]
	v_mfma_f32_16x16x32_bf16 v[122:125], v[130:133], v[158:161], v[122:125]
	v_mfma_f32_16x16x32_bf16 v[122:125], v[142:145], v[162:165], v[122:125]
	v_mfma_f32_16x16x32_bf16 v[126:129], v[118:121], v[162:165], v[126:129]
	v_mfma_f32_16x16x32_bf16 v[126:129], v[106:109], v[158:161], v[126:129]
	v_mfma_f32_16x16x32_bf16 v[102:105], v[106:109], v[170:173], v[102:105]
	v_mfma_f32_16x16x32_bf16 v[102:105], v[118:121], v[174:177], v[102:105]
	v_mfma_f32_16x16x32_bf16 v[94:97], v[142:145], v[174:177], v[94:97]
	v_mfma_f32_16x16x32_bf16 v[94:97], v[130:133], v[170:173], v[94:97]
	v_mfma_f32_16x16x32_bf16 v[70:73], v[130:133], v[178:181], v[70:73]
	v_mfma_f32_16x16x32_bf16 v[70:73], v[142:145], v[190:193], v[70:73]
	v_mfma_f32_16x16x32_bf16 v[74:77], v[118:121], v[190:193], v[74:77]
	v_mfma_f32_16x16x32_bf16 v[74:77], v[106:109], v[178:181], v[74:77]
	s_setprio 0
	s_barrier
	ds_read_b128 v[150:153], v234 offset:16384
	ds_read_b128 v[154:157], v234 offset:17408
	ds_read_b128 v[158:161], v234 offset:18432
	ds_read_b128 v[162:165], v234 offset:19456
	ds_read_b128 v[170:173], v234 offset:20480
	ds_read_b128 v[174:177], v234 offset:21504
	ds_read_b128 v[178:181], v234 offset:22528
	ds_read_b128 v[190:193], v234 offset:23552
	s_add_i32 s18, s49, s26
	s_mov_b32 m0, s18
	s_nop 0
	global_load_lds_dwordx4 v194, s[22:23]
	s_add_i32 m0, s18, 0x2000
	s_add_u32 s18, s22, 0x160000
	s_addc_u32 s19, s23, 0
	s_add_i32 s49, s50, s26
	global_load_lds_dwordx4 v204, s[22:23]
	s_mov_b32 m0, s49
	s_nop 0
	global_load_lds_dwordx4 v194, s[18:19]
	s_add_i32 m0, s49, 0x2000
	s_nop 0
	global_load_lds_dwordx4 v204, s[18:19]
	s_waitcnt vmcnt(6)
	s_waitcnt lgkmcnt(0)
	v_mfma_f32_16x16x32_bf16 v[62:65], v[66:69], v[150:153], v[62:65]
	v_mfma_f32_16x16x32_bf16 v[62:65], v[78:81], v[154:157], v[62:65]
	v_mfma_f32_16x16x32_bf16 v[58:61], v[98:101], v[154:157], v[58:61]
	v_mfma_f32_16x16x32_bf16 v[58:61], v[86:89], v[150:153], v[58:61]
	s_barrier
	s_setprio 1
	v_mfma_f32_16x16x32_bf16 v[42:45], v[86:89], v[158:161], v[42:45]
	v_mfma_f32_16x16x32_bf16 v[42:45], v[98:101], v[162:165], v[42:45]
	v_mfma_f32_16x16x32_bf16 v[46:49], v[78:81], v[162:165], v[46:49]
	v_mfma_f32_16x16x32_bf16 v[46:49], v[66:69], v[158:161], v[46:49]
	v_mfma_f32_16x16x32_bf16 v[30:33], v[66:69], v[170:173], v[30:33]
	v_mfma_f32_16x16x32_bf16 v[30:33], v[78:81], v[174:177], v[30:33]
	v_mfma_f32_16x16x32_bf16 v[26:29], v[98:101], v[174:177], v[26:29]
	v_mfma_f32_16x16x32_bf16 v[26:29], v[86:89], v[170:173], v[26:29]
	v_mfma_f32_16x16x32_bf16 v[10:13], v[86:89], v[178:181], v[10:13]
	v_mfma_f32_16x16x32_bf16 v[10:13], v[98:101], v[190:193], v[10:13]
	v_mfma_f32_16x16x32_bf16 v[14:17], v[78:81], v[190:193], v[14:17]
	v_mfma_f32_16x16x32_bf16 v[14:17], v[66:69], v[178:181], v[14:17]
	v_mfma_f32_16x16x32_bf16 v[54:57], v[106:109], v[150:153], v[54:57]
	v_mfma_f32_16x16x32_bf16 v[54:57], v[118:121], v[154:157], v[54:57]
	v_mfma_f32_16x16x32_bf16 v[50:53], v[142:145], v[154:157], v[50:53]
	v_mfma_f32_16x16x32_bf16 v[50:53], v[130:133], v[150:153], v[50:53]
	v_mfma_f32_16x16x32_bf16 v[34:37], v[130:133], v[158:161], v[34:37]
	v_mfma_f32_16x16x32_bf16 v[34:37], v[142:145], v[162:165], v[34:37]
	v_mfma_f32_16x16x32_bf16 v[38:41], v[118:121], v[162:165], v[38:41]
	v_mfma_f32_16x16x32_bf16 v[38:41], v[106:109], v[158:161], v[38:41]
	v_mfma_f32_16x16x32_bf16 v[22:25], v[106:109], v[170:173], v[22:25]
	v_mfma_f32_16x16x32_bf16 v[22:25], v[118:121], v[174:177], v[22:25]
	v_mfma_f32_16x16x32_bf16 v[18:21], v[142:145], v[174:177], v[18:21]
	v_mfma_f32_16x16x32_bf16 v[18:21], v[130:133], v[170:173], v[18:21]
	v_mfma_f32_16x16x32_bf16 v[2:5], v[130:133], v[178:181], v[2:5]
	v_mfma_f32_16x16x32_bf16 v[2:5], v[142:145], v[190:193], v[2:5]
	v_mfma_f32_16x16x32_bf16 v[6:9], v[118:121], v[190:193], v[6:9]
	v_mfma_f32_16x16x32_bf16 v[6:9], v[106:109], v[178:181], v[6:9]
	s_setprio 0
	s_barrier
	s_mov_b32 m0, s28
	s_nop 0
	global_load_lds_dwordx4 v208, s[24:25]
	s_mov_b32 m0, s29
	s_nop 0
	global_load_lds_dwordx4 v206, s[24:25]
	ds_read_b128 v[66:69], v198 offset:32768
	ds_read_b128 v[78:81], v198 offset:33792
	ds_read_b128 v[86:89], v198 offset:34816
	ds_read_b128 v[98:101], v198 offset:35840
	ds_read_b128 v[106:109], v198 offset:49152
	ds_read_b128 v[118:121], v198 offset:50176
	ds_read_b128 v[130:133], v198 offset:51200
	ds_read_b128 v[142:145], v198 offset:52224
	ds_read_b128 v[150:153], v234 offset:32768
	ds_read_b128 v[154:157], v234 offset:33792
	ds_read_b128 v[158:161], v234 offset:34816
	ds_read_b128 v[162:165], v234 offset:35840
	ds_read_b128 v[170:173], v234 offset:36864
	ds_read_b128 v[174:177], v234 offset:37888
	ds_read_b128 v[178:181], v234 offset:38912
	ds_read_b128 v[190:193], v234 offset:39936
	s_add_i32 s49, 0, 0x18000
	s_add_i32 s50, 0, 0x1c000
	s_add_u32 s18, s24, 0x160000
	s_addc_u32 s19, s25, 0
	s_mov_b32 m0, s33
	s_nop 0
	global_load_lds_dwordx4 v208, s[18:19]
	s_mov_b32 m0, s37
	s_nop 0
	global_load_lds_dwordx4 v206, s[18:19]
	s_waitcnt vmcnt(8)
	s_waitcnt lgkmcnt(0)
	v_mfma_f32_16x16x32_bf16 v[186:189], v[66:69], v[150:153], v[186:189]
	v_mfma_f32_16x16x32_bf16 v[186:189], v[78:81], v[154:157], v[186:189]
	v_mfma_f32_16x16x32_bf16 v[182:185], v[98:101], v[154:157], v[182:185]
	v_mfma_f32_16x16x32_bf16 v[182:185], v[86:89], v[150:153], v[182:185]
	s_barrier
	s_setprio 1
	v_mfma_f32_16x16x32_bf16 v[134:137], v[86:89], v[158:161], v[134:137]
	v_mfma_f32_16x16x32_bf16 v[134:137], v[98:101], v[162:165], v[134:137]
	v_mfma_f32_16x16x32_bf16 v[138:141], v[78:81], v[162:165], v[138:141]
	v_mfma_f32_16x16x32_bf16 v[138:141], v[66:69], v[158:161], v[138:141]
	v_mfma_f32_16x16x32_bf16 v[114:117], v[66:69], v[170:173], v[114:117]
	v_mfma_f32_16x16x32_bf16 v[114:117], v[78:81], v[174:177], v[114:117]
	v_mfma_f32_16x16x32_bf16 v[110:113], v[98:101], v[174:177], v[110:113]
	v_mfma_f32_16x16x32_bf16 v[110:113], v[86:89], v[170:173], v[110:113]
	v_mfma_f32_16x16x32_bf16 v[82:85], v[86:89], v[178:181], v[82:85]
	v_mfma_f32_16x16x32_bf16 v[82:85], v[98:101], v[190:193], v[82:85]
	v_mfma_f32_16x16x32_bf16 v[90:93], v[78:81], v[190:193], v[90:93]
	v_mfma_f32_16x16x32_bf16 v[90:93], v[66:69], v[178:181], v[90:93]
	v_mfma_f32_16x16x32_bf16 v[166:169], v[106:109], v[150:153], v[166:169]
	v_mfma_f32_16x16x32_bf16 v[166:169], v[118:121], v[154:157], v[166:169]
	v_mfma_f32_16x16x32_bf16 v[146:149], v[142:145], v[154:157], v[146:149]
	v_mfma_f32_16x16x32_bf16 v[146:149], v[130:133], v[150:153], v[146:149]
	v_mfma_f32_16x16x32_bf16 v[122:125], v[130:133], v[158:161], v[122:125]
	v_mfma_f32_16x16x32_bf16 v[122:125], v[142:145], v[162:165], v[122:125]
	v_mfma_f32_16x16x32_bf16 v[126:129], v[118:121], v[162:165], v[126:129]
	v_mfma_f32_16x16x32_bf16 v[126:129], v[106:109], v[158:161], v[126:129]
	v_mfma_f32_16x16x32_bf16 v[102:105], v[106:109], v[170:173], v[102:105]
	v_mfma_f32_16x16x32_bf16 v[102:105], v[118:121], v[174:177], v[102:105]
	v_mfma_f32_16x16x32_bf16 v[94:97], v[142:145], v[174:177], v[94:97]
	v_mfma_f32_16x16x32_bf16 v[94:97], v[130:133], v[170:173], v[94:97]
	v_mfma_f32_16x16x32_bf16 v[70:73], v[130:133], v[178:181], v[70:73]
	v_mfma_f32_16x16x32_bf16 v[70:73], v[142:145], v[190:193], v[70:73]
	v_mfma_f32_16x16x32_bf16 v[74:77], v[118:121], v[190:193], v[74:77]
	v_mfma_f32_16x16x32_bf16 v[74:77], v[106:109], v[178:181], v[74:77]
	s_setprio 0
	s_barrier
	ds_read_b128 v[150:153], v234 offset:49152
	ds_read_b128 v[154:157], v234 offset:50176
	ds_read_b128 v[158:161], v234 offset:51200
	ds_read_b128 v[162:165], v234 offset:52224
	ds_read_b128 v[170:173], v234 offset:53248
	ds_read_b128 v[174:177], v234 offset:54272
	ds_read_b128 v[178:181], v234 offset:55296
	ds_read_b128 v[190:193], v234 offset:56320
	s_add_i32 s18, s49, s26
	s_add_u32 vcc_lo, s22, s94
	s_addc_u32 vcc_hi, s23, s95
	s_mov_b32 m0, s18
	s_nop 0
	global_load_lds_dwordx4 v194, vcc
	s_add_i32 m0, s18, 0x2000
	s_add_u32 s18, s22, 0x160080
	s_addc_u32 s19, s23, 0
	s_add_i32 s22, s50, s26
	global_load_lds_dwordx4 v204, vcc
	s_mov_b32 m0, s22
	s_nop 0
	global_load_lds_dwordx4 v194, s[18:19]
	s_add_i32 m0, s22, 0x2000
	s_nop 0
	global_load_lds_dwordx4 v204, s[18:19]
	s_waitcnt vmcnt(6)
	s_waitcnt lgkmcnt(0)
	v_mfma_f32_16x16x32_bf16 v[62:65], v[66:69], v[150:153], v[62:65]
	v_mfma_f32_16x16x32_bf16 v[62:65], v[78:81], v[154:157], v[62:65]
	v_mfma_f32_16x16x32_bf16 v[58:61], v[98:101], v[154:157], v[58:61]
	v_mfma_f32_16x16x32_bf16 v[58:61], v[86:89], v[150:153], v[58:61]
	s_barrier
	s_setprio 1
	v_mfma_f32_16x16x32_bf16 v[42:45], v[86:89], v[158:161], v[42:45]
	v_mfma_f32_16x16x32_bf16 v[42:45], v[98:101], v[162:165], v[42:45]
	v_mfma_f32_16x16x32_bf16 v[46:49], v[78:81], v[162:165], v[46:49]
	v_mfma_f32_16x16x32_bf16 v[46:49], v[66:69], v[158:161], v[46:49]
	v_mfma_f32_16x16x32_bf16 v[30:33], v[66:69], v[170:173], v[30:33]
	v_mfma_f32_16x16x32_bf16 v[30:33], v[78:81], v[174:177], v[30:33]
	v_mfma_f32_16x16x32_bf16 v[26:29], v[98:101], v[174:177], v[26:29]
	v_mfma_f32_16x16x32_bf16 v[26:29], v[86:89], v[170:173], v[26:29]
	v_mfma_f32_16x16x32_bf16 v[10:13], v[86:89], v[178:181], v[10:13]
	v_mfma_f32_16x16x32_bf16 v[10:13], v[98:101], v[190:193], v[10:13]
	s_add_i32 s48, s48, 2
	v_mfma_f32_16x16x32_bf16 v[14:17], v[78:81], v[190:193], v[14:17]
	v_mfma_f32_16x16x32_bf16 v[14:17], v[66:69], v[178:181], v[14:17]
	s_add_u32 s46, s46, 0x100
	v_mfma_f32_16x16x32_bf16 v[54:57], v[106:109], v[150:153], v[54:57]
	v_mfma_f32_16x16x32_bf16 v[54:57], v[118:121], v[154:157], v[54:57]
	s_addc_u32 s47, s47, 0
	v_mfma_f32_16x16x32_bf16 v[50:53], v[142:145], v[154:157], v[50:53]
	v_mfma_f32_16x16x32_bf16 v[50:53], v[130:133], v[150:153], v[50:53]
	s_cmpk_gt_u32 s48, 0x55
	v_mfma_f32_16x16x32_bf16 v[34:37], v[130:133], v[158:161], v[34:37]
	v_mfma_f32_16x16x32_bf16 v[34:37], v[142:145], v[162:165], v[34:37]
	s_mov_b64 s[18:19], s[20:21]
	v_mfma_f32_16x16x32_bf16 v[38:41], v[118:121], v[162:165], v[38:41]
	v_mfma_f32_16x16x32_bf16 v[38:41], v[106:109], v[158:161], v[38:41]
	v_mfma_f32_16x16x32_bf16 v[22:25], v[106:109], v[170:173], v[22:25]
	v_mfma_f32_16x16x32_bf16 v[22:25], v[118:121], v[174:177], v[22:25]
	v_mfma_f32_16x16x32_bf16 v[18:21], v[142:145], v[174:177], v[18:21]
	v_mfma_f32_16x16x32_bf16 v[18:21], v[130:133], v[170:173], v[18:21]
	v_mfma_f32_16x16x32_bf16 v[2:5], v[130:133], v[178:181], v[2:5]
	v_mfma_f32_16x16x32_bf16 v[2:5], v[142:145], v[190:193], v[2:5]
	v_mfma_f32_16x16x32_bf16 v[6:9], v[118:121], v[190:193], v[6:9]
	v_mfma_f32_16x16x32_bf16 v[6:9], v[106:109], v[178:181], v[6:9]
	s_setprio 0
	s_barrier
	s_cbranch_scc0 .LBB0_1441

.LBB0_1511:
	s_add_u32 vcc_lo, s18, 0xffea0000
	s_addc_u32 vcc_hi, s19, -1
	s_mov_b32 m0, s44
	s_nop 0
	global_load_lds_dwordx4 v210, vcc
	s_mov_b32 m0, s45
	s_nop 0
	global_load_lds_dwordx4 v212, vcc
	ds_read_b128 v[130:133], v235
	ds_read_b128 v[134:137], v235 offset:1024
	ds_read_b128 v[138:141], v235 offset:2048
	ds_read_b128 v[142:145], v235 offset:3072
	ds_read_b128 v[146:149], v235 offset:16384
	ds_read_b128 v[150:153], v235 offset:17408
	ds_read_b128 v[154:157], v235 offset:18432
	ds_read_b128 v[158:161], v235 offset:19456
	ds_read_b128 v[162:165], v237
	ds_read_b128 v[166:169], v237 offset:1024
	ds_read_b128 v[170:173], v237 offset:2048
	ds_read_b128 v[174:177], v237 offset:3072
	ds_read_b128 v[178:181], v237 offset:4096
	ds_read_b128 v[182:185], v237 offset:5120
	ds_read_b128 v[186:189], v237 offset:6144
	ds_read_b128 v[190:193], v237 offset:7168
	s_add_i32 s55, s26, 2
	s_add_u32 s24, s18, 0x100
	s_addc_u32 s25, s19, 0
	s_add_i32 s56, 0, 0x10000
	s_cmp_eq_u32 s15, s26
	s_cselect_b32 s29, s7, s25
	s_cselect_b32 s28, s6, s24
	s_cselect_b32 s27, s17, s54
	s_cselect_b32 s26, s16, s23
	s_add_i32 s57, 0, 0x14000
	s_add_i32 m0, s40, 0xc000
	s_nop 0
	global_load_lds_dwordx4 v210, s[18:19]
	s_add_i32 m0, s40, 0xe000
	s_nop 0
	global_load_lds_dwordx4 v212, s[18:19]
	s_waitcnt vmcnt(8)
	s_waitcnt lgkmcnt(0)
	v_mfma_f32_16x16x32_bf16 v[126:129], v[130:133], v[162:165], v[126:129]
	v_mfma_f32_16x16x32_bf16 v[126:129], v[134:137], v[166:169], v[126:129]
	v_mfma_f32_16x16x32_bf16 v[122:125], v[142:145], v[166:169], v[122:125]
	v_mfma_f32_16x16x32_bf16 v[122:125], v[138:141], v[162:165], v[122:125]
	s_barrier
	s_setprio 1
	v_mfma_f32_16x16x32_bf16 v[106:109], v[138:141], v[170:173], v[106:109]
	v_mfma_f32_16x16x32_bf16 v[106:109], v[142:145], v[174:177], v[106:109]
	v_mfma_f32_16x16x32_bf16 v[110:113], v[134:137], v[174:177], v[110:113]
	v_mfma_f32_16x16x32_bf16 v[110:113], v[130:133], v[170:173], v[110:113]
	v_mfma_f32_16x16x32_bf16 v[94:97], v[130:133], v[178:181], v[94:97]
	v_mfma_f32_16x16x32_bf16 v[94:97], v[134:137], v[182:185], v[94:97]
	v_mfma_f32_16x16x32_bf16 v[90:93], v[142:145], v[182:185], v[90:93]
	v_mfma_f32_16x16x32_bf16 v[90:93], v[138:141], v[178:181], v[90:93]
	v_mfma_f32_16x16x32_bf16 v[74:77], v[138:141], v[186:189], v[74:77]
	v_mfma_f32_16x16x32_bf16 v[74:77], v[142:145], v[190:193], v[74:77]
	v_mfma_f32_16x16x32_bf16 v[78:81], v[134:137], v[190:193], v[78:81]
	v_mfma_f32_16x16x32_bf16 v[78:81], v[130:133], v[186:189], v[78:81]
	v_mfma_f32_16x16x32_bf16 v[118:121], v[146:149], v[162:165], v[118:121]
	v_mfma_f32_16x16x32_bf16 v[118:121], v[150:153], v[166:169], v[118:121]
	v_mfma_f32_16x16x32_bf16 v[114:117], v[158:161], v[166:169], v[114:117]
	v_mfma_f32_16x16x32_bf16 v[114:117], v[154:157], v[162:165], v[114:117]
	v_mfma_f32_16x16x32_bf16 v[98:101], v[154:157], v[170:173], v[98:101]
	v_mfma_f32_16x16x32_bf16 v[98:101], v[158:161], v[174:177], v[98:101]
	v_mfma_f32_16x16x32_bf16 v[102:105], v[150:153], v[174:177], v[102:105]
	v_mfma_f32_16x16x32_bf16 v[102:105], v[146:149], v[170:173], v[102:105]
	v_mfma_f32_16x16x32_bf16 v[86:89], v[146:149], v[178:181], v[86:89]
	v_mfma_f32_16x16x32_bf16 v[86:89], v[150:153], v[182:185], v[86:89]
	v_mfma_f32_16x16x32_bf16 v[82:85], v[158:161], v[182:185], v[82:85]
	v_mfma_f32_16x16x32_bf16 v[82:85], v[154:157], v[178:181], v[82:85]
	v_mfma_f32_16x16x32_bf16 v[66:69], v[154:157], v[186:189], v[66:69]
	v_mfma_f32_16x16x32_bf16 v[66:69], v[158:161], v[190:193], v[66:69]
	v_mfma_f32_16x16x32_bf16 v[70:73], v[150:153], v[190:193], v[70:73]
	v_mfma_f32_16x16x32_bf16 v[70:73], v[146:149], v[186:189], v[70:73]
	s_setprio 0
	s_barrier
	ds_read_b128 v[162:165], v237 offset:16384
	ds_read_b128 v[166:169], v237 offset:17408
	ds_read_b128 v[170:173], v237 offset:18432
	ds_read_b128 v[174:177], v237 offset:19456
	ds_read_b128 v[178:181], v237 offset:20480
	ds_read_b128 v[182:185], v237 offset:21504
	ds_read_b128 v[186:189], v237 offset:22528
	ds_read_b128 v[190:193], v237 offset:23552
	s_add_i32 s18, s56, s39
	s_mov_b32 m0, s18
	s_nop 0
	global_load_lds_dwordx4 v194, s[26:27]
	s_add_i32 m0, s18, 0x2000
	s_add_u32 s18, s26, 0x160000
	s_addc_u32 s19, s27, 0
	s_add_i32 s56, s57, s39
	global_load_lds_dwordx4 v208, s[26:27]
	s_mov_b32 m0, s56
	s_nop 0
	global_load_lds_dwordx4 v194, s[18:19]
	s_add_i32 m0, s56, 0x2000
	s_nop 0
	global_load_lds_dwordx4 v208, s[18:19]
	s_waitcnt vmcnt(6)
	s_waitcnt lgkmcnt(0)
	v_mfma_f32_16x16x32_bf16 v[62:65], v[130:133], v[162:165], v[62:65]
	v_mfma_f32_16x16x32_bf16 v[62:65], v[134:137], v[166:169], v[62:65]
	v_mfma_f32_16x16x32_bf16 v[58:61], v[142:145], v[166:169], v[58:61]
	v_mfma_f32_16x16x32_bf16 v[58:61], v[138:141], v[162:165], v[58:61]
	s_barrier
	s_setprio 1
	v_mfma_f32_16x16x32_bf16 v[42:45], v[138:141], v[170:173], v[42:45]
	v_mfma_f32_16x16x32_bf16 v[42:45], v[142:145], v[174:177], v[42:45]
	v_mfma_f32_16x16x32_bf16 v[46:49], v[134:137], v[174:177], v[46:49]
	v_mfma_f32_16x16x32_bf16 v[46:49], v[130:133], v[170:173], v[46:49]
	v_mfma_f32_16x16x32_bf16 v[30:33], v[130:133], v[178:181], v[30:33]
	v_mfma_f32_16x16x32_bf16 v[30:33], v[134:137], v[182:185], v[30:33]
	v_mfma_f32_16x16x32_bf16 v[26:29], v[142:145], v[182:185], v[26:29]
	v_mfma_f32_16x16x32_bf16 v[26:29], v[138:141], v[178:181], v[26:29]
	v_mfma_f32_16x16x32_bf16 v[10:13], v[138:141], v[186:189], v[10:13]
	v_mfma_f32_16x16x32_bf16 v[10:13], v[142:145], v[190:193], v[10:13]
	v_mfma_f32_16x16x32_bf16 v[14:17], v[134:137], v[190:193], v[14:17]
	v_mfma_f32_16x16x32_bf16 v[14:17], v[130:133], v[186:189], v[14:17]
	v_mfma_f32_16x16x32_bf16 v[54:57], v[146:149], v[162:165], v[54:57]
	v_mfma_f32_16x16x32_bf16 v[54:57], v[150:153], v[166:169], v[54:57]
	v_mfma_f32_16x16x32_bf16 v[50:53], v[158:161], v[166:169], v[50:53]
	v_mfma_f32_16x16x32_bf16 v[50:53], v[154:157], v[162:165], v[50:53]
	v_mfma_f32_16x16x32_bf16 v[34:37], v[154:157], v[170:173], v[34:37]
	v_mfma_f32_16x16x32_bf16 v[34:37], v[158:161], v[174:177], v[34:37]
	v_mfma_f32_16x16x32_bf16 v[38:41], v[150:153], v[174:177], v[38:41]
	v_mfma_f32_16x16x32_bf16 v[38:41], v[146:149], v[170:173], v[38:41]
	v_mfma_f32_16x16x32_bf16 v[22:25], v[146:149], v[178:181], v[22:25]
	v_mfma_f32_16x16x32_bf16 v[22:25], v[150:153], v[182:185], v[22:25]
	v_mfma_f32_16x16x32_bf16 v[18:21], v[158:161], v[182:185], v[18:21]
	v_mfma_f32_16x16x32_bf16 v[18:21], v[154:157], v[178:181], v[18:21]
	v_mfma_f32_16x16x32_bf16 v[2:5], v[154:157], v[186:189], v[2:5]
	v_mfma_f32_16x16x32_bf16 v[2:5], v[158:161], v[190:193], v[2:5]
	v_mfma_f32_16x16x32_bf16 v[6:9], v[150:153], v[190:193], v[6:9]
	v_mfma_f32_16x16x32_bf16 v[6:9], v[146:149], v[186:189], v[6:9]
	s_setprio 0
	s_barrier
	s_mov_b32 m0, s40
	s_nop 0
	global_load_lds_dwordx4 v204, s[28:29]
	s_mov_b32 m0, s41
	s_nop 0
	global_load_lds_dwordx4 v206, s[28:29]
	ds_read_b128 v[130:133], v235 offset:32768
	ds_read_b128 v[134:137], v235 offset:33792
	ds_read_b128 v[138:141], v235 offset:34816
	ds_read_b128 v[142:145], v235 offset:35840
	ds_read_b128 v[146:149], v235 offset:49152
	ds_read_b128 v[150:153], v235 offset:50176
	ds_read_b128 v[154:157], v235 offset:51200
	ds_read_b128 v[158:161], v235 offset:52224
	ds_read_b128 v[162:165], v237 offset:32768
	ds_read_b128 v[166:169], v237 offset:33792
	ds_read_b128 v[170:173], v237 offset:34816
	ds_read_b128 v[174:177], v237 offset:35840
	ds_read_b128 v[178:181], v237 offset:36864
	ds_read_b128 v[182:185], v237 offset:37888
	ds_read_b128 v[186:189], v237 offset:38912
	ds_read_b128 v[190:193], v237 offset:39936
	s_add_i32 s56, 0, 0x18000
	s_add_i32 s57, 0, 0x1c000
	s_add_u32 s18, s28, 0x160000
	s_addc_u32 s19, s29, 0
	s_mov_b32 m0, s42
	s_nop 0
	global_load_lds_dwordx4 v204, s[18:19]
	s_mov_b32 m0, s43
	s_nop 0
	global_load_lds_dwordx4 v206, s[18:19]
	s_waitcnt vmcnt(8)
	s_waitcnt lgkmcnt(0)
	v_mfma_f32_16x16x32_bf16 v[126:129], v[130:133], v[162:165], v[126:129]
	v_mfma_f32_16x16x32_bf16 v[126:129], v[134:137], v[166:169], v[126:129]
	v_mfma_f32_16x16x32_bf16 v[122:125], v[142:145], v[166:169], v[122:125]
	v_mfma_f32_16x16x32_bf16 v[122:125], v[138:141], v[162:165], v[122:125]
	s_barrier
	s_setprio 1
	v_mfma_f32_16x16x32_bf16 v[106:109], v[138:141], v[170:173], v[106:109]
	v_mfma_f32_16x16x32_bf16 v[106:109], v[142:145], v[174:177], v[106:109]
	v_mfma_f32_16x16x32_bf16 v[110:113], v[134:137], v[174:177], v[110:113]
	v_mfma_f32_16x16x32_bf16 v[110:113], v[130:133], v[170:173], v[110:113]
	v_mfma_f32_16x16x32_bf16 v[94:97], v[130:133], v[178:181], v[94:97]
	v_mfma_f32_16x16x32_bf16 v[94:97], v[134:137], v[182:185], v[94:97]
	v_mfma_f32_16x16x32_bf16 v[90:93], v[142:145], v[182:185], v[90:93]
	v_mfma_f32_16x16x32_bf16 v[90:93], v[138:141], v[178:181], v[90:93]
	v_mfma_f32_16x16x32_bf16 v[74:77], v[138:141], v[186:189], v[74:77]
	v_mfma_f32_16x16x32_bf16 v[74:77], v[142:145], v[190:193], v[74:77]
	v_mfma_f32_16x16x32_bf16 v[78:81], v[134:137], v[190:193], v[78:81]
	v_mfma_f32_16x16x32_bf16 v[78:81], v[130:133], v[186:189], v[78:81]
	v_mfma_f32_16x16x32_bf16 v[118:121], v[146:149], v[162:165], v[118:121]
	v_mfma_f32_16x16x32_bf16 v[118:121], v[150:153], v[166:169], v[118:121]
	v_mfma_f32_16x16x32_bf16 v[114:117], v[158:161], v[166:169], v[114:117]
	v_mfma_f32_16x16x32_bf16 v[114:117], v[154:157], v[162:165], v[114:117]
	v_mfma_f32_16x16x32_bf16 v[98:101], v[154:157], v[170:173], v[98:101]
	v_mfma_f32_16x16x32_bf16 v[98:101], v[158:161], v[174:177], v[98:101]
	v_mfma_f32_16x16x32_bf16 v[102:105], v[150:153], v[174:177], v[102:105]
	v_mfma_f32_16x16x32_bf16 v[102:105], v[146:149], v[170:173], v[102:105]
	v_mfma_f32_16x16x32_bf16 v[86:89], v[146:149], v[178:181], v[86:89]
	v_mfma_f32_16x16x32_bf16 v[86:89], v[150:153], v[182:185], v[86:89]
	v_mfma_f32_16x16x32_bf16 v[82:85], v[158:161], v[182:185], v[82:85]
	v_mfma_f32_16x16x32_bf16 v[82:85], v[154:157], v[178:181], v[82:85]
	v_mfma_f32_16x16x32_bf16 v[66:69], v[154:157], v[186:189], v[66:69]
	v_mfma_f32_16x16x32_bf16 v[66:69], v[158:161], v[190:193], v[66:69]
	v_mfma_f32_16x16x32_bf16 v[70:73], v[150:153], v[190:193], v[70:73]
	v_mfma_f32_16x16x32_bf16 v[70:73], v[146:149], v[186:189], v[70:73]
	s_setprio 0
	s_barrier
	ds_read_b128 v[162:165], v237 offset:49152
	ds_read_b128 v[166:169], v237 offset:50176
	ds_read_b128 v[170:173], v237 offset:51200
	ds_read_b128 v[174:177], v237 offset:52224
	ds_read_b128 v[178:181], v237 offset:53248
	ds_read_b128 v[182:185], v237 offset:54272
	ds_read_b128 v[186:189], v237 offset:55296
	ds_read_b128 v[190:193], v237 offset:56320
	s_add_i32 s18, s56, s39
	s_add_u32 vcc_lo, s26, s94
	s_addc_u32 vcc_hi, s27, s95
	s_mov_b32 m0, s18
	s_nop 0
	global_load_lds_dwordx4 v194, vcc
	s_add_i32 m0, s18, 0x2000
	s_add_u32 s18, s26, 0x160080
	s_addc_u32 s19, s27, 0
	s_add_i32 s26, s57, s39
	global_load_lds_dwordx4 v208, vcc
	s_mov_b32 m0, s26
	s_nop 0
	global_load_lds_dwordx4 v194, s[18:19]
	s_add_i32 m0, s26, 0x2000
	s_nop 0
	global_load_lds_dwordx4 v208, s[18:19]
	s_waitcnt vmcnt(6)
	s_waitcnt lgkmcnt(0)
	v_mfma_f32_16x16x32_bf16 v[62:65], v[130:133], v[162:165], v[62:65]
	v_mfma_f32_16x16x32_bf16 v[62:65], v[134:137], v[166:169], v[62:65]
	v_mfma_f32_16x16x32_bf16 v[58:61], v[142:145], v[166:169], v[58:61]
	v_mfma_f32_16x16x32_bf16 v[58:61], v[138:141], v[162:165], v[58:61]
	s_barrier
	s_setprio 1
	v_mfma_f32_16x16x32_bf16 v[42:45], v[138:141], v[170:173], v[42:45]
	v_mfma_f32_16x16x32_bf16 v[42:45], v[142:145], v[174:177], v[42:45]
	v_mfma_f32_16x16x32_bf16 v[46:49], v[134:137], v[174:177], v[46:49]
	v_mfma_f32_16x16x32_bf16 v[46:49], v[130:133], v[170:173], v[46:49]
	v_mfma_f32_16x16x32_bf16 v[30:33], v[130:133], v[178:181], v[30:33]
	v_mfma_f32_16x16x32_bf16 v[30:33], v[134:137], v[182:185], v[30:33]
	v_mfma_f32_16x16x32_bf16 v[26:29], v[142:145], v[182:185], v[26:29]
	v_mfma_f32_16x16x32_bf16 v[26:29], v[138:141], v[178:181], v[26:29]
	v_mfma_f32_16x16x32_bf16 v[10:13], v[138:141], v[186:189], v[10:13]
	v_mfma_f32_16x16x32_bf16 v[10:13], v[142:145], v[190:193], v[10:13]
	s_add_u32 s23, s23, 0x100
	v_mfma_f32_16x16x32_bf16 v[14:17], v[134:137], v[190:193], v[14:17]
	v_mfma_f32_16x16x32_bf16 v[14:17], v[130:133], v[186:189], v[14:17]
	s_addc_u32 s54, s54, 0
	v_mfma_f32_16x16x32_bf16 v[54:57], v[146:149], v[162:165], v[54:57]
	v_mfma_f32_16x16x32_bf16 v[54:57], v[150:153], v[166:169], v[54:57]
	s_cmp_ge_i32 s55, s21
	v_mfma_f32_16x16x32_bf16 v[50:53], v[158:161], v[166:169], v[50:53]
	v_mfma_f32_16x16x32_bf16 v[50:53], v[154:157], v[162:165], v[50:53]
	s_mov_b64 s[18:19], s[24:25]
	v_mfma_f32_16x16x32_bf16 v[34:37], v[154:157], v[170:173], v[34:37]
	v_mfma_f32_16x16x32_bf16 v[34:37], v[158:161], v[174:177], v[34:37]
	s_mov_b32 s26, s55
	v_mfma_f32_16x16x32_bf16 v[38:41], v[150:153], v[174:177], v[38:41]
	v_mfma_f32_16x16x32_bf16 v[38:41], v[146:149], v[170:173], v[38:41]
	v_mfma_f32_16x16x32_bf16 v[22:25], v[146:149], v[178:181], v[22:25]
	v_mfma_f32_16x16x32_bf16 v[22:25], v[150:153], v[182:185], v[22:25]
	v_mfma_f32_16x16x32_bf16 v[18:21], v[158:161], v[182:185], v[18:21]
	v_mfma_f32_16x16x32_bf16 v[18:21], v[154:157], v[178:181], v[18:21]
	v_mfma_f32_16x16x32_bf16 v[2:5], v[154:157], v[186:189], v[2:5]
	v_mfma_f32_16x16x32_bf16 v[2:5], v[158:161], v[190:193], v[2:5]
	v_mfma_f32_16x16x32_bf16 v[6:9], v[150:153], v[190:193], v[6:9]
	v_mfma_f32_16x16x32_bf16 v[6:9], v[146:149], v[186:189], v[6:9]
	s_setprio 0
	s_barrier
	s_cbranch_scc0 .LBB0_1511
	s_and_b64 vcc, exec, s[12:13]
	s_cbranch_vccz .LBB0_1514
